# v8 + each MFMA segment signals its closing barrier 2 MFMAs before the end of the burst (the last 2 MFMAs issue after the barrier, beside the partner wave's first ones)
# baseline (speedup 1.0000x reference)
; #define PG8_STAGE(bufoff, gbase, voff) do { _Pragma("unroll") for (int _i = 0; _i < 2; ++_i) \
;         __builtin_amdgcn_global_load_lds((const unsigned*)((const char*)(gbase) + (voff)[_i]), (LAS unsigned*)(lds + (bufoff) + ldsw + _i * 8192), 16, 0, 0); } while (0)
; #define PG8_LDA(dst, b, h) do { _Pragma("unroll") for (int m = 0; m < 4; ++m) _Pragma("unroll") for (int k = 0; k < 2; ++k) dst[m][k] = *(const LAS bf16x8*)(lds + PG8_SA(b, h) + aoff + m * 2048 + k * KOFF); } while (0)
; #define PG8_LDB(dst, b, h) do { _Pragma("unroll") for (int n = 0; n < 2; ++n) _Pragma("unroll") for (int k = 0; k < 2; ++k) dst[n][k] = *(const LAS bf16x8*)(lds + PG8_SB(b, h) + boff + n * 2048 + k * KOFF); } while (0)
; #define PG8_WAIT_V(n) asm volatile("s_waitcnt vmcnt(" #n ")" ::: "memory")
; #define PG8_WAIT_L(n) asm volatile("s_waitcnt lgkmcnt(" #n ")" ::: "memory")
; #define PG8_BAR __builtin_amdgcn_s_barrier()
; #define PG8_SCHED __builtin_amdgcn_sched_barrier(0)
; template <class Epi, bool ALIGN_EPI = true, bool FP8 = false>
; __device__ __forceinline__ void gemm_phase(LAS unsigned char* lds, const Gemm g, const StaticOrder& S, const Epi& E, const int wid) {
;     ...
;             const char* a1 = cA + (size_t)(t + 1) * kstep;
;             const char* a2 = last ? nA : cA + (size_t)(t + 2) * kstep; const char* b2 = last ? nB : cB + (size_t)(t + 2) * kstep;
;             const char* a3 = a2 + kstep; const char* b3 = b2 + kstep;
;             PG8_LDB(B0, 0, 0); PG8_LDB(B1, 0, 1); PG8_SCHED; PG8_LDA(At, 0, 0); PG8_STAGE(PG8_SA(1, 1), a1 + hstep, voffA);
;             PG8_WAIT_V(8); PG8_WAIT_L(0); PG8_BAR; PG8_MMA(0, 0, At, B0); PG8_MMA(0, 1, At, B1); PG8_BAR; PG8_SCHED;
;             PG8_LDA(At, 0, 1); PG8_STAGE(PG8_SB(0, 0), b2, voffB); PG8_STAGE(PG8_SB(0, 1), b2 + hstep, voffB); PG8_STAGE(PG8_SA(0, 0), a2, voffA);
;             PG8_WAIT_V(8); PG8_WAIT_L(0); PG8_BAR; PG8_MMA(1, 0, At, B0); PG8_MMA(1, 1, At, B1); PG8_BAR; PG8_SCHED;
.LBB0_506:
	ds_read_b128 v[146:149], v137
	ds_read_b128 v[154:157], v137 offset:1024
	ds_read_b128 v[158:161], v137 offset:2048
	ds_read_b128 v[162:165], v137 offset:3072
	ds_read_b128 v[166:169], v152
	ds_read_b128 v[170:173], v152 offset:1024
	ds_read_b128 v[174:177], v152 offset:2048
	ds_read_b128 v[178:181], v152 offset:3072
	s_add_i32 s52, s34, 2
	s_add_u32 s35, s30, 0xfff80080
	s_addc_u32 s36, s31, -1
	s_cmp_eq_u32 s39, s34
	s_cselect_b32 s34, s38, s42
	s_cselect_b32 s37, s3, s36
	s_cselect_b32 s36, s23, s35
	s_cselect_b32 s35, s25, s43
	v_lshl_add_u64 v[214:215], s[30:31], 0, v[140:141]
	s_add_i32 m0, s75, 0xc000
	ds_read_b128 v[182:185], v153
	ds_read_b128 v[186:189], v153 offset:1024
	ds_read_b128 v[190:193], v153 offset:2048
	ds_read_b128 v[194:197], v153 offset:3072
	ds_read_b128 v[198:201], v153 offset:4096
	ds_read_b128 v[202:205], v153 offset:5120
	ds_read_b128 v[206:209], v153 offset:6144
	ds_read_b128 v[210:213], v153 offset:7168
	global_load_lds_dwordx4 v[214:215], off
	v_lshl_add_u64 v[214:215], s[30:31], 0, v[142:143]
	s_add_i32 m0, s75, 0xe000
	s_nop 0
	global_load_lds_dwordx4 v[214:215], off
	s_setprio 1
	s_waitcnt vmcnt(8) lgkmcnt(0)
	s_barrier
	v_mfma_f32_16x16x32_bf16 v[124:127], v[146:149], v[182:185], v[124:127]
	v_mfma_f32_16x16x32_bf16 v[120:123], v[158:161], v[182:185], v[120:123]
	v_mfma_f32_16x16x32_bf16 v[108:111], v[146:149], v[190:193], v[108:111]
	v_mfma_f32_16x16x32_bf16 v[104:107], v[158:161], v[190:193], v[104:107]
	v_mfma_f32_16x16x32_bf16 v[92:95], v[146:149], v[198:201], v[92:95]
	v_mfma_f32_16x16x32_bf16 v[88:91], v[158:161], v[198:201], v[88:91]
	v_mfma_f32_16x16x32_bf16 v[76:79], v[146:149], v[206:209], v[76:79]
	v_mfma_f32_16x16x32_bf16 v[72:75], v[158:161], v[206:209], v[72:75]
	v_mfma_f32_16x16x32_bf16 v[124:127], v[154:157], v[186:189], v[124:127]
	v_mfma_f32_16x16x32_bf16 v[120:123], v[162:165], v[186:189], v[120:123]
	v_mfma_f32_16x16x32_bf16 v[108:111], v[154:157], v[194:197], v[108:111]
	v_mfma_f32_16x16x32_bf16 v[104:107], v[162:165], v[194:197], v[104:107]
	v_mfma_f32_16x16x32_bf16 v[92:95], v[154:157], v[202:205], v[92:95]
	v_mfma_f32_16x16x32_bf16 v[88:91], v[162:165], v[202:205], v[88:91]
	v_mfma_f32_16x16x32_bf16 v[76:79], v[154:157], v[210:213], v[76:79]
	v_mfma_f32_16x16x32_bf16 v[72:75], v[162:165], v[210:213], v[72:75]
	v_mfma_f32_16x16x32_bf16 v[116:119], v[166:169], v[182:185], v[116:119]
	v_mfma_f32_16x16x32_bf16 v[112:115], v[174:177], v[182:185], v[112:115]
	v_mfma_f32_16x16x32_bf16 v[100:103], v[166:169], v[190:193], v[100:103]
	v_mfma_f32_16x16x32_bf16 v[96:99], v[174:177], v[190:193], v[96:99]
	v_mfma_f32_16x16x32_bf16 v[84:87], v[166:169], v[198:201], v[84:87]
	v_mfma_f32_16x16x32_bf16 v[80:83], v[174:177], v[198:201], v[80:83]
	v_mfma_f32_16x16x32_bf16 v[68:71], v[166:169], v[206:209], v[68:71]
	v_mfma_f32_16x16x32_bf16 v[64:67], v[174:177], v[206:209], v[64:67]
	v_mfma_f32_16x16x32_bf16 v[116:119], v[170:173], v[186:189], v[116:119]
	v_mfma_f32_16x16x32_bf16 v[112:115], v[178:181], v[186:189], v[112:115]
	v_mfma_f32_16x16x32_bf16 v[100:103], v[170:173], v[194:197], v[100:103]
	v_mfma_f32_16x16x32_bf16 v[96:99], v[178:181], v[194:197], v[96:99]
	v_mfma_f32_16x16x32_bf16 v[84:87], v[170:173], v[202:205], v[84:87]
	v_mfma_f32_16x16x32_bf16 v[80:83], v[178:181], v[202:205], v[80:83]
	s_barrier
	v_mfma_f32_16x16x32_bf16 v[68:71], v[170:173], v[210:213], v[68:71]
	v_mfma_f32_16x16x32_bf16 v[64:67], v[178:181], v[210:213], v[64:67]
	s_setprio 0
	s_add_i32 s54, s86, s48
	v_lshl_add_u64 v[214:215], s[34:35], 0, v[132:133]
	s_mov_b32 m0, s54
	ds_read_b128 v[182:185], v153 offset:16384
	ds_read_b128 v[186:189], v153 offset:17408
	ds_read_b128 v[190:193], v153 offset:18432
	ds_read_b128 v[194:197], v153 offset:19456
	ds_read_b128 v[198:201], v153 offset:20480
	ds_read_b128 v[202:205], v153 offset:21504
	ds_read_b128 v[206:209], v153 offset:22528
	ds_read_b128 v[210:213], v153 offset:23552
	global_load_lds_dwordx4 v[214:215], off
	s_add_i32 m0, s54, 0x2000
	s_add_u32 s64, s34, 0x80000
	v_lshl_add_u64 v[216:217], s[34:35], 0, v[128:129]
	s_addc_u32 s65, s35, 0
	s_add_i32 s54, s87, s48
	global_load_lds_dwordx4 v[216:217], off
	v_lshl_add_u64 v[218:219], s[64:65], 0, v[132:133]
	s_mov_b32 m0, s54
	v_lshl_add_u64 v[220:221], s[36:37], 0, v[130:131]
	global_load_lds_dwordx4 v[218:219], off
	v_lshl_add_u64 v[218:219], s[64:65], 0, v[128:129]
	s_add_i32 m0, s54, 0x2000
	s_nop 0
	global_load_lds_dwordx4 v[218:219], off
	v_lshl_add_u64 v[218:219], s[36:37], 0, v[134:135]
	s_mov_b32 m0, s75
	s_nop 0
	global_load_lds_dwordx4 v[218:219], off
	s_mov_b32 m0, s76
	s_nop 0
	global_load_lds_dwordx4 v[220:221], off
	s_setprio 1
	s_waitcnt vmcnt(8) lgkmcnt(0)
	s_barrier
; #define PG8_STAGE(bufoff, gbase, voff) do { _Pragma("unroll") for (int _i = 0; _i < 2; ++_i) \
;         __builtin_amdgcn_global_load_lds((const unsigned*)((const char*)(gbase) + (voff)[_i]), (LAS unsigned*)(lds + (bufoff) + ldsw + _i * 8192), 16, 0, 0); } while (0)
; #define PG8_LDA(dst, b, h) do { _Pragma("unroll") for (int m = 0; m < 4; ++m) _Pragma("unroll") for (int k = 0; k < 2; ++k) dst[m][k] = *(const LAS bf16x8*)(lds + PG8_SA(b, h) + aoff + m * 2048 + k * KOFF); } while (0)
; #define PG8_LDB(dst, b, h) do { _Pragma("unroll") for (int n = 0; n < 2; ++n) _Pragma("unroll") for (int k = 0; k < 2; ++k) dst[n][k] = *(const LAS bf16x8*)(lds + PG8_SB(b, h) + boff + n * 2048 + k * KOFF); } while (0)
; #define PG8_WAIT_V(n) asm volatile("s_waitcnt vmcnt(" #n ")" ::: "memory")
; #define PG8_WAIT_L(n) asm volatile("s_waitcnt lgkmcnt(" #n ")" ::: "memory")
; #define PG8_BAR __builtin_amdgcn_s_barrier()
; #define PG8_SCHED __builtin_amdgcn_sched_barrier(0)
; template <class Epi, bool ALIGN_EPI = true, bool FP8 = false>
; __device__ __forceinline__ void gemm_phase(LAS unsigned char* lds, const Gemm g, const StaticOrder& S, const Epi& E, const int wid) {
;     ...
;             PG8_WAIT_V(8); PG8_WAIT_L(0); PG8_BAR; PG8_MMA(1, 0, At, B0); PG8_MMA(1, 1, At, B1); PG8_BAR; PG8_SCHED;
;             PG8_LDB(B0, 1, 0); PG8_LDB(B1, 1, 1); PG8_SCHED; PG8_LDA(At, 1, 0); PG8_STAGE(PG8_SA(0, 1), a2 + hstep, voffA);
;             PG8_WAIT_V(8); PG8_WAIT_L(0); PG8_BAR; PG8_MMA(0, 0, At, B0); PG8_MMA(0, 1, At, B1); PG8_BAR; PG8_SCHED;
	v_mfma_f32_16x16x32_bf16 v[60:63], v[146:149], v[182:185], v[60:63]
	v_mfma_f32_16x16x32_bf16 v[56:59], v[158:161], v[182:185], v[56:59]
	v_mfma_f32_16x16x32_bf16 v[44:47], v[146:149], v[190:193], v[44:47]
	v_mfma_f32_16x16x32_bf16 v[40:43], v[158:161], v[190:193], v[40:43]
	v_mfma_f32_16x16x32_bf16 v[28:31], v[146:149], v[198:201], v[28:31]
	v_mfma_f32_16x16x32_bf16 v[24:27], v[158:161], v[198:201], v[24:27]
	v_mfma_f32_16x16x32_bf16 v[12:15], v[146:149], v[206:209], v[12:15]
	v_mfma_f32_16x16x32_bf16 v[8:11], v[158:161], v[206:209], v[8:11]
	v_mfma_f32_16x16x32_bf16 v[60:63], v[154:157], v[186:189], v[60:63]
	v_mfma_f32_16x16x32_bf16 v[56:59], v[162:165], v[186:189], v[56:59]
	v_mfma_f32_16x16x32_bf16 v[44:47], v[154:157], v[194:197], v[44:47]
	v_mfma_f32_16x16x32_bf16 v[40:43], v[162:165], v[194:197], v[40:43]
	v_mfma_f32_16x16x32_bf16 v[28:31], v[154:157], v[202:205], v[28:31]
	v_mfma_f32_16x16x32_bf16 v[24:27], v[162:165], v[202:205], v[24:27]
	v_mfma_f32_16x16x32_bf16 v[12:15], v[154:157], v[210:213], v[12:15]
	v_mfma_f32_16x16x32_bf16 v[8:11], v[162:165], v[210:213], v[8:11]
	v_mfma_f32_16x16x32_bf16 v[52:55], v[166:169], v[182:185], v[52:55]
	v_mfma_f32_16x16x32_bf16 v[48:51], v[174:177], v[182:185], v[48:51]
	v_mfma_f32_16x16x32_bf16 v[36:39], v[166:169], v[190:193], v[36:39]
	v_mfma_f32_16x16x32_bf16 v[32:35], v[174:177], v[190:193], v[32:35]
	v_mfma_f32_16x16x32_bf16 v[20:23], v[166:169], v[198:201], v[20:23]
	v_mfma_f32_16x16x32_bf16 v[16:19], v[174:177], v[198:201], v[16:19]
	v_mfma_f32_16x16x32_bf16 v[4:7], v[166:169], v[206:209], v[4:7]
	v_mfma_f32_16x16x32_bf16 v[0:3], v[174:177], v[206:209], v[0:3]
	v_mfma_f32_16x16x32_bf16 v[52:55], v[170:173], v[186:189], v[52:55]
	v_mfma_f32_16x16x32_bf16 v[48:51], v[178:181], v[186:189], v[48:51]
	v_mfma_f32_16x16x32_bf16 v[36:39], v[170:173], v[194:197], v[36:39]
	v_mfma_f32_16x16x32_bf16 v[32:35], v[178:181], v[194:197], v[32:35]
	v_mfma_f32_16x16x32_bf16 v[20:23], v[170:173], v[202:205], v[20:23]
	v_mfma_f32_16x16x32_bf16 v[16:19], v[178:181], v[202:205], v[16:19]
	s_barrier
	v_mfma_f32_16x16x32_bf16 v[4:7], v[170:173], v[210:213], v[4:7]
	v_mfma_f32_16x16x32_bf16 v[0:3], v[178:181], v[210:213], v[0:3]
	s_setprio 0
	s_add_i32 s54, 0, 0x18000
	s_add_i32 s64, 0, 0x1c000
	v_add_u32_e32 v162, s54, v150
	v_add_u32_e32 v178, s64, v150
	ds_read_b128 v[146:149], v162
	ds_read_b128 v[154:157], v162 offset:1024
	ds_read_b128 v[158:161], v162 offset:2048
	ds_read_b128 v[162:165], v162 offset:3072
	ds_read_b128 v[166:169], v178
	ds_read_b128 v[170:173], v178 offset:1024
	ds_read_b128 v[174:177], v178 offset:2048
	ds_read_b128 v[178:181], v178 offset:3072
	s_add_u32 s36, s36, 0x80000
	s_addc_u32 s37, s37, 0
	s_mov_b32 m0, s77
	v_lshl_add_u64 v[222:223], s[36:37], 0, v[134:135]
	ds_read_b128 v[182:185], v153 offset:32768
	ds_read_b128 v[186:189], v153 offset:33792
	ds_read_b128 v[190:193], v153 offset:34816
	ds_read_b128 v[194:197], v153 offset:35840
	ds_read_b128 v[198:201], v153 offset:36864
	ds_read_b128 v[202:205], v153 offset:37888
	ds_read_b128 v[206:209], v153 offset:38912
	ds_read_b128 v[210:213], v153 offset:39936
	global_load_lds_dwordx4 v[222:223], off
	v_lshl_add_u64 v[222:223], s[36:37], 0, v[130:131]
	s_mov_b32 m0, s78
	s_nop 0
	global_load_lds_dwordx4 v[222:223], off
	s_setprio 1
	s_waitcnt vmcnt(8) lgkmcnt(0)
	s_barrier
	v_mfma_f32_16x16x32_bf16 v[124:127], v[146:149], v[182:185], v[124:127]
	v_mfma_f32_16x16x32_bf16 v[120:123], v[158:161], v[182:185], v[120:123]
	v_mfma_f32_16x16x32_bf16 v[108:111], v[146:149], v[190:193], v[108:111]
	v_mfma_f32_16x16x32_bf16 v[104:107], v[158:161], v[190:193], v[104:107]
	v_mfma_f32_16x16x32_bf16 v[92:95], v[146:149], v[198:201], v[92:95]
	v_mfma_f32_16x16x32_bf16 v[88:91], v[158:161], v[198:201], v[88:91]
	v_mfma_f32_16x16x32_bf16 v[76:79], v[146:149], v[206:209], v[76:79]
	v_mfma_f32_16x16x32_bf16 v[72:75], v[158:161], v[206:209], v[72:75]
	v_mfma_f32_16x16x32_bf16 v[124:127], v[154:157], v[186:189], v[124:127]
	v_mfma_f32_16x16x32_bf16 v[120:123], v[162:165], v[186:189], v[120:123]
	v_mfma_f32_16x16x32_bf16 v[108:111], v[154:157], v[194:197], v[108:111]
	v_mfma_f32_16x16x32_bf16 v[104:107], v[162:165], v[194:197], v[104:107]
	v_mfma_f32_16x16x32_bf16 v[92:95], v[154:157], v[202:205], v[92:95]
	v_mfma_f32_16x16x32_bf16 v[88:91], v[162:165], v[202:205], v[88:91]
	v_mfma_f32_16x16x32_bf16 v[76:79], v[154:157], v[210:213], v[76:79]
	v_mfma_f32_16x16x32_bf16 v[72:75], v[162:165], v[210:213], v[72:75]
	v_mfma_f32_16x16x32_bf16 v[116:119], v[166:169], v[182:185], v[116:119]
	v_mfma_f32_16x16x32_bf16 v[112:115], v[174:177], v[182:185], v[112:115]
	v_mfma_f32_16x16x32_bf16 v[100:103], v[166:169], v[190:193], v[100:103]
	v_mfma_f32_16x16x32_bf16 v[96:99], v[174:177], v[190:193], v[96:99]
	v_mfma_f32_16x16x32_bf16 v[84:87], v[166:169], v[198:201], v[84:87]
	v_mfma_f32_16x16x32_bf16 v[80:83], v[174:177], v[198:201], v[80:83]
	v_mfma_f32_16x16x32_bf16 v[68:71], v[166:169], v[206:209], v[68:71]
	v_mfma_f32_16x16x32_bf16 v[64:67], v[174:177], v[206:209], v[64:67]
	v_mfma_f32_16x16x32_bf16 v[116:119], v[170:173], v[186:189], v[116:119]
	v_mfma_f32_16x16x32_bf16 v[112:115], v[178:181], v[186:189], v[112:115]
	v_mfma_f32_16x16x32_bf16 v[100:103], v[170:173], v[194:197], v[100:103]
	v_mfma_f32_16x16x32_bf16 v[96:99], v[178:181], v[194:197], v[96:99]
	v_mfma_f32_16x16x32_bf16 v[84:87], v[170:173], v[202:205], v[84:87]
	v_mfma_f32_16x16x32_bf16 v[80:83], v[178:181], v[202:205], v[80:83]
	s_barrier
; #define PG8_STAGE(bufoff, gbase, voff) do { _Pragma("unroll") for (int _i = 0; _i < 2; ++_i) \
;         __builtin_amdgcn_global_load_lds((const unsigned*)((const char*)(gbase) + (voff)[_i]), (LAS unsigned*)(lds + (bufoff) + ldsw + _i * 8192), 16, 0, 0); } while (0)
; #define PG8_LDA(dst, b, h) do { _Pragma("unroll") for (int m = 0; m < 4; ++m) _Pragma("unroll") for (int k = 0; k < 2; ++k) dst[m][k] = *(const LAS bf16x8*)(lds + PG8_SA(b, h) + aoff + m * 2048 + k * KOFF); } while (0)
; #define PG8_WAIT_V(n) asm volatile("s_waitcnt vmcnt(" #n ")" ::: "memory")
; #define PG8_WAIT_L(n) asm volatile("s_waitcnt lgkmcnt(" #n ")" ::: "memory")
; #define PG8_BAR __builtin_amdgcn_s_barrier()
; #define PG8_SCHED __builtin_amdgcn_sched_barrier(0)
; template <class Epi, bool ALIGN_EPI = true, bool FP8 = false>
; __device__ __forceinline__ void gemm_phase(LAS unsigned char* lds, const Gemm g, const StaticOrder& S, const Epi& E, const int wid) {
;     ...
;             PG8_WAIT_V(8); PG8_WAIT_L(0); PG8_BAR; PG8_MMA(0, 0, At, B0); PG8_MMA(0, 1, At, B1); PG8_BAR; PG8_SCHED;
;             PG8_LDA(At, 1, 1); PG8_STAGE(PG8_SB(1, 0), b3, voffB); PG8_STAGE(PG8_SB(1, 1), b3 + hstep, voffB); PG8_STAGE(PG8_SA(1, 0), a3, voffA);
;             PG8_WAIT_V(8); PG8_WAIT_L(0); PG8_BAR; PG8_MMA(1, 0, At, B0); PG8_MMA(1, 1, At, B1); PG8_BAR; PG8_SCHED;
;         }
	v_mfma_f32_16x16x32_bf16 v[68:71], v[170:173], v[210:213], v[68:71]
	v_mfma_f32_16x16x32_bf16 v[64:67], v[178:181], v[210:213], v[64:67]
	s_setprio 0
	s_add_i32 s36, s54, s48
	v_lshl_add_u64 v[214:215], v[214:215], 0, s[16:17]
	s_mov_b32 m0, s36
	ds_read_b128 v[182:185], v153 offset:49152
	ds_read_b128 v[186:189], v153 offset:50176
	ds_read_b128 v[190:193], v153 offset:51200
	ds_read_b128 v[194:197], v153 offset:52224
	ds_read_b128 v[198:201], v153 offset:53248
	ds_read_b128 v[202:205], v153 offset:54272
	ds_read_b128 v[206:209], v153 offset:55296
	ds_read_b128 v[210:213], v153 offset:56320
	global_load_lds_dwordx4 v[214:215], off
	s_add_i32 m0, s36, 0x2000
	s_add_u32 s34, s34, 0x80080
	v_lshl_add_u64 v[214:215], v[216:217], 0, s[16:17]
	s_addc_u32 s35, s35, 0
	s_add_i32 s36, s64, s48
	global_load_lds_dwordx4 v[214:215], off
	v_lshl_add_u64 v[214:215], s[34:35], 0, v[132:133]
	s_mov_b32 m0, s36
	s_nop 0
	global_load_lds_dwordx4 v[214:215], off
	v_lshl_add_u64 v[214:215], s[34:35], 0, v[128:129]
	s_add_i32 m0, s36, 0x2000
	s_nop 0
	global_load_lds_dwordx4 v[214:215], off
	v_lshl_add_u64 v[214:215], v[218:219], 0, s[16:17]
	s_mov_b32 m0, s83
	s_nop 0
	global_load_lds_dwordx4 v[214:215], off
	v_lshl_add_u64 v[214:215], v[220:221], 0, s[16:17]
	s_mov_b32 m0, s84
	s_nop 0
	global_load_lds_dwordx4 v[214:215], off
	s_setprio 1
	s_waitcnt vmcnt(8) lgkmcnt(0)
	s_barrier
	v_mfma_f32_16x16x32_bf16 v[60:63], v[146:149], v[182:185], v[60:63]
	v_mfma_f32_16x16x32_bf16 v[56:59], v[158:161], v[182:185], v[56:59]
	v_mfma_f32_16x16x32_bf16 v[44:47], v[146:149], v[190:193], v[44:47]
	v_mfma_f32_16x16x32_bf16 v[40:43], v[158:161], v[190:193], v[40:43]
	v_mfma_f32_16x16x32_bf16 v[28:31], v[146:149], v[198:201], v[28:31]
	v_mfma_f32_16x16x32_bf16 v[24:27], v[158:161], v[198:201], v[24:27]
	v_mfma_f32_16x16x32_bf16 v[12:15], v[146:149], v[206:209], v[12:15]
	v_mfma_f32_16x16x32_bf16 v[8:11], v[158:161], v[206:209], v[8:11]
	v_mfma_f32_16x16x32_bf16 v[60:63], v[154:157], v[186:189], v[60:63]
	v_mfma_f32_16x16x32_bf16 v[56:59], v[162:165], v[186:189], v[56:59]
	v_mfma_f32_16x16x32_bf16 v[44:47], v[154:157], v[194:197], v[44:47]
	v_mfma_f32_16x16x32_bf16 v[40:43], v[162:165], v[194:197], v[40:43]
	v_mfma_f32_16x16x32_bf16 v[28:31], v[154:157], v[202:205], v[28:31]
	v_mfma_f32_16x16x32_bf16 v[24:27], v[162:165], v[202:205], v[24:27]
	v_mfma_f32_16x16x32_bf16 v[12:15], v[154:157], v[210:213], v[12:15]
	v_mfma_f32_16x16x32_bf16 v[8:11], v[162:165], v[210:213], v[8:11]
	v_mfma_f32_16x16x32_bf16 v[52:55], v[166:169], v[182:185], v[52:55]
	v_mfma_f32_16x16x32_bf16 v[48:51], v[174:177], v[182:185], v[48:51]
	v_mfma_f32_16x16x32_bf16 v[36:39], v[166:169], v[190:193], v[36:39]
	v_mfma_f32_16x16x32_bf16 v[32:35], v[174:177], v[190:193], v[32:35]
	v_mfma_f32_16x16x32_bf16 v[20:23], v[166:169], v[198:201], v[20:23]
	v_mfma_f32_16x16x32_bf16 v[16:19], v[174:177], v[198:201], v[16:19]
	v_mfma_f32_16x16x32_bf16 v[4:7], v[166:169], v[206:209], v[4:7]
	v_mfma_f32_16x16x32_bf16 v[0:3], v[174:177], v[206:209], v[0:3]
	v_mfma_f32_16x16x32_bf16 v[52:55], v[170:173], v[186:189], v[52:55]
	v_mfma_f32_16x16x32_bf16 v[48:51], v[178:181], v[186:189], v[48:51]
	v_mfma_f32_16x16x32_bf16 v[36:39], v[170:173], v[194:197], v[36:39]
	v_mfma_f32_16x16x32_bf16 v[32:35], v[178:181], v[194:197], v[32:35]
	v_mfma_f32_16x16x32_bf16 v[20:23], v[170:173], v[202:205], v[20:23]
	v_mfma_f32_16x16x32_bf16 v[16:19], v[178:181], v[202:205], v[16:19]
	s_barrier
	v_mfma_f32_16x16x32_bf16 v[4:7], v[170:173], v[210:213], v[4:7]
	v_mfma_f32_16x16x32_bf16 v[0:3], v[178:181], v[210:213], v[0:3]
	s_setprio 0
	s_add_u32 s30, s30, 0x100
	s_addc_u32 s31, s31, 0
	s_add_u32 s42, s42, 0x100
	s_addc_u32 s43, s43, 0
	s_cmp_ge_u32 s52, s9
	s_mov_b32 s34, s52
	s_cbranch_scc0 .LBB0_506
	s_and_b64 vcc, exec, s[12:13]
	s_cbranch_vccz .LBB0_509

; #define PG8_STAGE(bufoff, gbase, voff) do { _Pragma("unroll") for (int _i = 0; _i < 2; ++_i) \
;         __builtin_amdgcn_global_load_lds((const unsigned*)((const char*)(gbase) + (voff)[_i]), (LAS unsigned*)(lds + (bufoff) + ldsw + _i * 8192), 16, 0, 0); } while (0)
; #define PG8_LDA(dst, b, h) do { _Pragma("unroll") for (int m = 0; m < 4; ++m) _Pragma("unroll") for (int k = 0; k < 2; ++k) dst[m][k] = *(const LAS bf16x8*)(lds + PG8_SA(b, h) + aoff + m * 2048 + k * KOFF); } while (0)
; #define PG8_LDB(dst, b, h) do { _Pragma("unroll") for (int n = 0; n < 2; ++n) _Pragma("unroll") for (int k = 0; k < 2; ++k) dst[n][k] = *(const LAS bf16x8*)(lds + PG8_SB(b, h) + boff + n * 2048 + k * KOFF); } while (0)
; #define PG8_WAIT_V(n) asm volatile("s_waitcnt vmcnt(" #n ")" ::: "memory")
; #define PG8_WAIT_L(n) asm volatile("s_waitcnt lgkmcnt(" #n ")" ::: "memory")
; #define PG8_BAR __builtin_amdgcn_s_barrier()
; #define PG8_SCHED __builtin_amdgcn_sched_barrier(0)
; template <class Epi, bool ALIGN_EPI = true, bool FP8 = false>
; __device__ __forceinline__ void gemm_phase(LAS unsigned char* lds, const Gemm g, const StaticOrder& S, const Epi& E, const int wid) {
;     ...
;             const char* a1 = cA + (size_t)(t + 1) * kstep;
;             const char* a2 = last ? nA : cA + (size_t)(t + 2) * kstep; const char* b2 = last ? nB : cB + (size_t)(t + 2) * kstep;
;             const char* a3 = a2 + kstep; const char* b3 = b2 + kstep;
;             PG8_LDB(B0, 0, 0); PG8_LDB(B1, 0, 1); PG8_SCHED; PG8_LDA(At, 0, 0); PG8_STAGE(PG8_SA(1, 1), a1 + hstep, voffA);
;             PG8_WAIT_V(8); PG8_WAIT_L(0); PG8_BAR; PG8_MMA(0, 0, At, B0); PG8_MMA(0, 1, At, B1); PG8_BAR; PG8_SCHED;
;             PG8_LDA(At, 0, 1); PG8_STAGE(PG8_SB(0, 0), b2, voffB); PG8_STAGE(PG8_SB(0, 1), b2 + hstep, voffB); PG8_STAGE(PG8_SA(0, 0), a2, voffA);
;             PG8_WAIT_V(8); PG8_WAIT_L(0); PG8_BAR; PG8_MMA(1, 0, At, B0); PG8_MMA(1, 1, At, B1); PG8_BAR; PG8_SCHED;
.LBB0_572:
	ds_read_b128 v[152:155], v190
	ds_read_b128 v[156:159], v190 offset:1024
	ds_read_b128 v[144:147], v190 offset:2048
	ds_read_b128 v[148:151], v190 offset:3072
	ds_read_b128 v[136:139], v191
	ds_read_b128 v[140:143], v191 offset:1024
	ds_read_b128 v[128:131], v191 offset:2048
	ds_read_b128 v[132:135], v191 offset:3072
	s_add_i32 s3, s34, 2
	s_add_u32 s35, s30, 0xfffc0080
	s_addc_u32 s36, s31, -1
	s_cmp_eq_u32 s86, s34
	s_cselect_b32 s34, s85, s87
	s_cselect_b32 s37, s21, s36
	s_cselect_b32 s36, s23, s35
	s_cselect_b32 s35, s84, s88
	v_lshl_add_u64 v[220:221], s[30:31], 0, v[170:171]
	s_add_i32 m0, s27, 0xc000
	ds_read_b128 v[178:181], v192
	ds_read_b128 v[182:185], v192 offset:1024
	ds_read_b128 v[196:199], v192 offset:2048
	ds_read_b128 v[200:203], v192 offset:3072
	ds_read_b128 v[204:207], v192 offset:4096
	ds_read_b128 v[208:211], v192 offset:5120
	ds_read_b128 v[212:215], v192 offset:6144
	ds_read_b128 v[216:219], v192 offset:7168
	global_load_lds_dwordx4 v[220:221], off
	v_lshl_add_u64 v[220:221], s[30:31], 0, v[172:173]
	s_add_i32 m0, s27, 0xe000
	s_nop 0
	global_load_lds_dwordx4 v[220:221], off
	s_setprio 1
	s_waitcnt vmcnt(8) lgkmcnt(0)
	s_barrier
	v_mfma_f32_16x16x128_f8f6f4 v[120:123], v[152:159], v[178:185], v[120:123]
	v_mfma_f32_16x16x128_f8f6f4 v[124:127], v[144:151], v[178:185], v[124:127]
	v_mfma_f32_16x16x128_f8f6f4 v[112:115], v[152:159], v[196:203], v[112:115]
	v_mfma_f32_16x16x128_f8f6f4 v[116:119], v[144:151], v[196:203], v[116:119]
	v_mfma_f32_16x16x128_f8f6f4 v[104:107], v[152:159], v[204:211], v[104:107]
	v_mfma_f32_16x16x128_f8f6f4 v[108:111], v[144:151], v[204:211], v[108:111]
	v_mfma_f32_16x16x128_f8f6f4 v[88:91], v[152:159], v[212:219], v[88:91]
	v_mfma_f32_16x16x128_f8f6f4 v[92:95], v[144:151], v[212:219], v[92:95]
	v_mfma_f32_16x16x128_f8f6f4 v[96:99], v[136:143], v[178:185], v[96:99]
	v_mfma_f32_16x16x128_f8f6f4 v[100:103], v[128:135], v[178:185], v[100:103]
	v_mfma_f32_16x16x128_f8f6f4 v[80:83], v[136:143], v[196:203], v[80:83]
	v_mfma_f32_16x16x128_f8f6f4 v[84:87], v[128:135], v[196:203], v[84:87]
	v_mfma_f32_16x16x128_f8f6f4 v[72:75], v[136:143], v[204:211], v[72:75]
	v_mfma_f32_16x16x128_f8f6f4 v[76:79], v[128:135], v[204:211], v[76:79]
	s_barrier
	v_mfma_f32_16x16x128_f8f6f4 v[64:67], v[136:143], v[212:219], v[64:67]
	v_mfma_f32_16x16x128_f8f6f4 v[68:71], v[128:135], v[212:219], v[68:71]
	s_setprio 0
	s_add_i32 s42, s75, s48
	v_lshl_add_u64 v[178:179], s[34:35], 0, v[164:165]
	s_mov_b32 m0, s42
	ds_read_b128 v[196:199], v192 offset:16384
	ds_read_b128 v[200:203], v192 offset:17408
	ds_read_b128 v[204:207], v192 offset:18432
	ds_read_b128 v[208:211], v192 offset:19456
	ds_read_b128 v[212:215], v192 offset:20480
	ds_read_b128 v[216:219], v192 offset:21504
	ds_read_b128 v[220:223], v192 offset:22528
	ds_read_b128 v[224:227], v192 offset:23552
	global_load_lds_dwordx4 v[178:179], off
	s_add_i32 m0, s42, 0x2000
	s_add_u32 s42, s34, 0x40000
	v_lshl_add_u64 v[180:181], s[34:35], 0, v[160:161]
	s_addc_u32 s43, s35, 0
	s_add_i32 s52, s76, s48
	global_load_lds_dwordx4 v[180:181], off
	v_lshl_add_u64 v[182:183], s[42:43], 0, v[164:165]
	s_mov_b32 m0, s52
	v_lshl_add_u64 v[184:185], s[36:37], 0, v[162:163]
	global_load_lds_dwordx4 v[182:183], off
	v_lshl_add_u64 v[182:183], s[42:43], 0, v[160:161]
	s_add_i32 m0, s52, 0x2000
	s_nop 0
	global_load_lds_dwordx4 v[182:183], off
	v_lshl_add_u64 v[182:183], s[36:37], 0, v[166:167]
	s_mov_b32 m0, s27
	s_nop 0
	global_load_lds_dwordx4 v[182:183], off
	s_mov_b32 m0, s55
	s_nop 0
	global_load_lds_dwordx4 v[184:185], off
	s_setprio 1
	s_waitcnt vmcnt(8) lgkmcnt(0)
	s_barrier
	v_mfma_f32_16x16x128_f8f6f4 v[56:59], v[152:159], v[196:203], v[56:59]
	v_mfma_f32_16x16x128_f8f6f4 v[60:63], v[144:151], v[196:203], v[60:63]
	v_mfma_f32_16x16x128_f8f6f4 v[48:51], v[152:159], v[204:211], v[48:51]
	v_mfma_f32_16x16x128_f8f6f4 v[52:55], v[144:151], v[204:211], v[52:55]
	v_mfma_f32_16x16x128_f8f6f4 v[40:43], v[152:159], v[212:219], v[40:43]
	v_mfma_f32_16x16x128_f8f6f4 v[44:47], v[144:151], v[212:219], v[44:47]
	v_mfma_f32_16x16x128_f8f6f4 v[228:231], v[152:159], v[220:227], v[24:27]
	v_mfma_f32_16x16x128_f8f6f4 v[232:235], v[144:151], v[220:227], v[28:31]
	v_mfma_f32_16x16x128_f8f6f4 v[236:239], v[136:143], v[196:203], v[32:35]
	v_mfma_f32_16x16x128_f8f6f4 v[240:243], v[128:135], v[196:203], v[36:39]
	v_mfma_f32_16x16x128_f8f6f4 v[244:247], v[136:143], v[204:211], v[16:19]
	v_mfma_f32_16x16x128_f8f6f4 v[204:207], v[128:135], v[204:211], v[20:23]
	v_mfma_f32_16x16x128_f8f6f4 v[208:211], v[136:143], v[212:219], v[8:11]
	v_mfma_f32_16x16x128_f8f6f4 v[212:215], v[128:135], v[212:219], v[12:15]
	s_barrier
	v_mfma_f32_16x16x128_f8f6f4 v[216:219], v[136:143], v[220:227], v[0:3]
	v_mfma_f32_16x16x128_f8f6f4 v[220:223], v[128:135], v[220:227], v[4:7]
	s_setprio 0
	s_add_i32 s42, 0, 0x18000
	s_add_i32 s43, 0, 0x1c000
	s_nop 0
	v_add_u32_e32 v12, s42, v187
	v_add_u32_e32 v16, s43, v187
	ds_read_b128 v[0:3], v12
	ds_read_b128 v[4:7], v12 offset:1024
	ds_read_b128 v[8:11], v12 offset:2048
	ds_read_b128 v[12:15], v12 offset:3072
	ds_read_b128 v[128:131], v16
	ds_read_b128 v[132:135], v16 offset:1024
	ds_read_b128 v[136:139], v16 offset:2048
	ds_read_b128 v[140:143], v16 offset:3072
	s_add_u32 s36, s36, 0x40000
	s_addc_u32 s37, s37, 0
	s_mov_b32 m0, s64
	v_lshl_add_u64 v[152:153], s[36:37], 0, v[166:167]
	ds_read_b128 v[16:19], v192 offset:32768
	ds_read_b128 v[20:23], v192 offset:33792
	ds_read_b128 v[24:27], v192 offset:34816
	ds_read_b128 v[28:31], v192 offset:35840
	ds_read_b128 v[32:35], v192 offset:36864
	ds_read_b128 v[36:39], v192 offset:37888
	ds_read_b128 v[144:147], v192 offset:38912
	ds_read_b128 v[148:151], v192 offset:39936
	global_load_lds_dwordx4 v[152:153], off
	v_lshl_add_u64 v[152:153], s[36:37], 0, v[162:163]
	s_mov_b32 m0, s65
	s_nop 0
	global_load_lds_dwordx4 v[152:153], off
	s_setprio 1
	s_waitcnt vmcnt(8) lgkmcnt(0)
	s_barrier
; #define PG8_STAGE(bufoff, gbase, voff) do { _Pragma("unroll") for (int _i = 0; _i < 2; ++_i) \
;         __builtin_amdgcn_global_load_lds((const unsigned*)((const char*)(gbase) + (voff)[_i]), (LAS unsigned*)(lds + (bufoff) + ldsw + _i * 8192), 16, 0, 0); } while (0)
; #define PG8_LDA(dst, b, h) do { _Pragma("unroll") for (int m = 0; m < 4; ++m) _Pragma("unroll") for (int k = 0; k < 2; ++k) dst[m][k] = *(const LAS bf16x8*)(lds + PG8_SA(b, h) + aoff + m * 2048 + k * KOFF); } while (0)
; #define PG8_WAIT_V(n) asm volatile("s_waitcnt vmcnt(" #n ")" ::: "memory")
; #define PG8_WAIT_L(n) asm volatile("s_waitcnt lgkmcnt(" #n ")" ::: "memory")
; #define PG8_BAR __builtin_amdgcn_s_barrier()
; #define PG8_SCHED __builtin_amdgcn_sched_barrier(0)
; template <class Epi, bool ALIGN_EPI = true, bool FP8 = false>
; __device__ __forceinline__ void gemm_phase(LAS unsigned char* lds, const Gemm g, const StaticOrder& S, const Epi& E, const int wid) {
;     ...
;             PG8_WAIT_V(8); PG8_WAIT_L(0); PG8_BAR; PG8_MMA(0, 0, At, B0); PG8_MMA(0, 1, At, B1); PG8_BAR; PG8_SCHED;
;             PG8_LDA(At, 1, 1); PG8_STAGE(PG8_SB(1, 0), b3, voffB); PG8_STAGE(PG8_SB(1, 1), b3 + hstep, voffB); PG8_STAGE(PG8_SA(1, 0), a3, voffA);
;             PG8_WAIT_V(8); PG8_WAIT_L(0); PG8_BAR; PG8_MMA(1, 0, At, B0); PG8_MMA(1, 1, At, B1); PG8_BAR; PG8_SCHED;
;         }
	v_mfma_f32_16x16x128_f8f6f4 v[120:123], v[0:7], v[16:23], v[120:123]
	v_mfma_f32_16x16x128_f8f6f4 v[124:127], v[8:15], v[16:23], v[124:127]
	v_mfma_f32_16x16x128_f8f6f4 v[112:115], v[0:7], v[24:31], v[112:115]
	v_mfma_f32_16x16x128_f8f6f4 v[116:119], v[8:15], v[24:31], v[116:119]
	v_mfma_f32_16x16x128_f8f6f4 v[104:107], v[0:7], v[32:39], v[104:107]
	v_mfma_f32_16x16x128_f8f6f4 v[108:111], v[8:15], v[32:39], v[108:111]
	v_mfma_f32_16x16x128_f8f6f4 v[88:91], v[0:7], v[144:151], v[88:91]
	v_mfma_f32_16x16x128_f8f6f4 v[92:95], v[8:15], v[144:151], v[92:95]
	v_mfma_f32_16x16x128_f8f6f4 v[96:99], v[128:135], v[16:23], v[96:99]
	v_mfma_f32_16x16x128_f8f6f4 v[100:103], v[136:143], v[16:23], v[100:103]
	v_mfma_f32_16x16x128_f8f6f4 v[80:83], v[128:135], v[24:31], v[80:83]
	v_mfma_f32_16x16x128_f8f6f4 v[84:87], v[136:143], v[24:31], v[84:87]
	v_mfma_f32_16x16x128_f8f6f4 v[72:75], v[128:135], v[32:39], v[72:75]
	v_mfma_f32_16x16x128_f8f6f4 v[76:79], v[136:143], v[32:39], v[76:79]
	s_barrier
	v_mfma_f32_16x16x128_f8f6f4 v[64:67], v[128:135], v[144:151], v[64:67]
	v_mfma_f32_16x16x128_f8f6f4 v[68:71], v[136:143], v[144:151], v[68:71]
	s_setprio 0
	s_add_i32 s36, s42, s48
	v_lshl_add_u64 v[24:25], v[178:179], 0, s[8:9]
	s_mov_b32 m0, s36
	ds_read_b128 v[16:19], v192 offset:49152
	ds_read_b128 v[20:23], v192 offset:50176
	ds_read_b128 v[144:147], v192 offset:51200
	ds_read_b128 v[148:151], v192 offset:52224
	ds_read_b128 v[152:155], v192 offset:53248
	ds_read_b128 v[156:159], v192 offset:54272
	ds_read_b128 v[196:199], v192 offset:55296
	ds_read_b128 v[200:203], v192 offset:56320
	global_load_lds_dwordx4 v[24:25], off
	s_add_i32 m0, s36, 0x2000
	s_add_u32 s34, s34, 0x40080
	v_lshl_add_u64 v[24:25], v[180:181], 0, s[8:9]
	s_addc_u32 s35, s35, 0
	s_add_i32 s36, s43, s48
	global_load_lds_dwordx4 v[24:25], off
	v_lshl_add_u64 v[24:25], s[34:35], 0, v[164:165]
	s_mov_b32 m0, s36
	s_nop 0
	global_load_lds_dwordx4 v[24:25], off
	v_lshl_add_u64 v[24:25], s[34:35], 0, v[160:161]
	s_add_i32 m0, s36, 0x2000
	s_nop 0
	global_load_lds_dwordx4 v[24:25], off
	v_lshl_add_u64 v[24:25], v[182:183], 0, s[8:9]
	s_mov_b32 m0, s70
	s_nop 0
	global_load_lds_dwordx4 v[24:25], off
	v_lshl_add_u64 v[24:25], v[184:185], 0, s[8:9]
	s_mov_b32 m0, s71
	s_nop 0
	global_load_lds_dwordx4 v[24:25], off
	s_setprio 1
	s_waitcnt vmcnt(8) lgkmcnt(0)
	s_barrier
	v_mfma_f32_16x16x128_f8f6f4 v[56:59], v[0:7], v[16:23], v[56:59]
	v_mfma_f32_16x16x128_f8f6f4 v[60:63], v[8:15], v[16:23], v[60:63]
	v_mfma_f32_16x16x128_f8f6f4 v[48:51], v[0:7], v[144:151], v[48:51]
	v_mfma_f32_16x16x128_f8f6f4 v[52:55], v[8:15], v[144:151], v[52:55]
	v_mfma_f32_16x16x128_f8f6f4 v[40:43], v[0:7], v[152:159], v[40:43]
	v_mfma_f32_16x16x128_f8f6f4 v[44:47], v[8:15], v[152:159], v[44:47]
	v_mfma_f32_16x16x128_f8f6f4 v[24:27], v[0:7], v[196:203], v[228:231]
	v_mfma_f32_16x16x128_f8f6f4 v[28:31], v[8:15], v[196:203], v[232:235]
	v_mfma_f32_16x16x128_f8f6f4 v[32:35], v[128:135], v[16:23], v[236:239]
	v_mfma_f32_16x16x128_f8f6f4 v[36:39], v[136:143], v[16:23], v[240:243]
	v_mfma_f32_16x16x128_f8f6f4 v[16:19], v[128:135], v[144:151], v[244:247]
	v_mfma_f32_16x16x128_f8f6f4 v[20:23], v[136:143], v[144:151], v[204:207]
	v_mfma_f32_16x16x128_f8f6f4 v[8:11], v[128:135], v[152:159], v[208:211]
	v_mfma_f32_16x16x128_f8f6f4 v[12:15], v[136:143], v[152:159], v[212:215]
	s_barrier
	v_mfma_f32_16x16x128_f8f6f4 v[0:3], v[128:135], v[196:203], v[216:219]
	v_mfma_f32_16x16x128_f8f6f4 v[4:7], v[136:143], v[196:203], v[220:223]
	s_setprio 0
	s_add_u32 s30, s30, 0x100
	s_addc_u32 s31, s31, 0
	s_add_u32 s87, s87, 0x100
	s_addc_u32 s88, s88, 0
	s_cmp_ge_u32 s3, s83
	s_mov_b32 s34, s3
	s_cbranch_scc0 .LBB0_572
;     __device__ __forceinline__ void operator()(const Acc& acc, const Unit& u, int wr, int wc, int fr, int fq) const {
;     ...
;                         const f32x4 v0 = acc[ai][bj][m][0] * QS, v1 = acc[ai][bj][m][1] * QS;
; template <class Epi, bool ALIGN_EPI = true, bool FP8 = false>
; __device__ __forceinline__ void gemm_phase(LAS unsigned char* lds, const Gemm g, const StaticOrder& S, const Epi& E, const int wid) {
;     ...
;         if constexpr (FP8) {
; #pragma unroll
;             for (int a = 0; a < 2; ++a)
; #pragma unroll
;                 for (int b = 0; b < 2; ++b)
; #pragma unroll
;                     for (int m = 0; m < 4; ++m) { const f32x8 c_ = acc8[a][b][m]; acc[a][b][m][0] = __builtin_shufflevector(c_, c_, 0, 1, 2, 3); acc[a][b][m][1] = __builtin_shufflevector(c_, c_, 4, 5, 6, 7); }
;         }
	v_pk_mul_f32 v[122:123], v[122:123], s[14:15] op_sel_hi:[1,0]
	v_pk_mul_f32 v[128:129], v[120:121], s[14:15] op_sel_hi:[1,0]
	v_pk_mul_f32 v[120:121], v[126:127], s[14:15] op_sel_hi:[1,0]
	v_pk_mul_f32 v[124:125], v[124:125], s[14:15] op_sel_hi:[1,0]
	v_pk_mul_f32 v[132:133], v[98:99], s[14:15] op_sel_hi:[1,0]
	v_pk_mul_f32 v[136:137], v[96:97], s[14:15] op_sel_hi:[1,0]
	v_pk_mul_f32 v[130:131], v[102:103], s[14:15] op_sel_hi:[1,0]
	v_pk_mul_f32 v[134:135], v[100:101], s[14:15] op_sel_hi:[1,0]
	v_pk_mul_f32 v[100:101], v[114:115], s[14:15] op_sel_hi:[1,0]
	v_pk_mul_f32 v[112:113], v[112:113], s[14:15] op_sel_hi:[1,0]
	v_pk_mul_f32 v[96:97], v[118:119], s[14:15] op_sel_hi:[1,0]
	v_pk_mul_f32 v[102:103], v[116:117], s[14:15] op_sel_hi:[1,0]
	v_pk_mul_f32 v[116:117], v[82:83], s[14:15] op_sel_hi:[1,0]
	v_pk_mul_f32 v[126:127], v[80:81], s[14:15] op_sel_hi:[1,0]
	v_pk_mul_f32 v[114:115], v[86:87], s[14:15] op_sel_hi:[1,0]
	v_pk_mul_f32 v[118:119], v[84:85], s[14:15] op_sel_hi:[1,0]
	v_pk_mul_f32 v[82:83], v[106:107], s[14:15] op_sel_hi:[1,0]
	v_pk_mul_f32 v[86:87], v[104:105], s[14:15] op_sel_hi:[1,0]
	v_pk_mul_f32 v[80:81], v[110:111], s[14:15] op_sel_hi:[1,0]
	v_pk_mul_f32 v[84:85], v[108:109], s[14:15] op_sel_hi:[1,0]
	v_pk_mul_f32 v[104:105], v[74:75], s[14:15] op_sel_hi:[1,0]
	v_pk_mul_f32 v[108:109], v[72:73], s[14:15] op_sel_hi:[1,0]
	v_pk_mul_f32 v[98:99], v[78:79], s[14:15] op_sel_hi:[1,0]
	v_pk_mul_f32 v[106:107], v[76:77], s[14:15] op_sel_hi:[1,0]
	v_pk_mul_f32 v[74:75], v[90:91], s[14:15] op_sel_hi:[1,0]
	v_pk_mul_f32 v[78:79], v[88:89], s[14:15] op_sel_hi:[1,0]
	v_pk_mul_f32 v[72:73], v[94:95], s[14:15] op_sel_hi:[1,0]
	v_pk_mul_f32 v[76:77], v[92:93], s[14:15] op_sel_hi:[1,0]
	v_pk_mul_f32 v[66:67], v[66:67], s[14:15] op_sel_hi:[1,0]
	v_pk_mul_f32 v[88:89], v[64:65], s[14:15] op_sel_hi:[1,0]
	v_pk_mul_f32 v[64:65], v[70:71], s[14:15] op_sel_hi:[1,0]
	v_pk_mul_f32 v[68:69], v[68:69], s[14:15] op_sel_hi:[1,0]
	v_pk_mul_f32 v[58:59], v[58:59], s[14:15] op_sel_hi:[1,0]
	v_pk_mul_f32 v[70:71], v[56:57], s[14:15] op_sel_hi:[1,0]
	v_pk_mul_f32 v[56:57], v[62:63], s[14:15] op_sel_hi:[1,0]
	v_pk_mul_f32 v[60:61], v[60:61], s[14:15] op_sel_hi:[1,0]
	v_pk_mul_f32 v[92:93], v[34:35], s[14:15] op_sel_hi:[1,0]
	v_pk_mul_f32 v[110:111], v[32:33], s[14:15] op_sel_hi:[1,0]
	v_pk_mul_f32 v[90:91], v[38:39], s[14:15] op_sel_hi:[1,0]
	v_pk_mul_f32 v[94:95], v[36:37], s[14:15] op_sel_hi:[1,0]
	v_pk_mul_f32 v[36:37], v[50:51], s[14:15] op_sel_hi:[1,0]
	v_pk_mul_f32 v[48:49], v[48:49], s[14:15] op_sel_hi:[1,0]
	v_pk_mul_f32 v[32:33], v[54:55], s[14:15] op_sel_hi:[1,0]
	v_pk_mul_f32 v[38:39], v[52:53], s[14:15] op_sel_hi:[1,0]
	v_pk_mul_f32 v[52:53], v[18:19], s[14:15] op_sel_hi:[1,0]
	v_pk_mul_f32 v[62:63], v[16:17], s[14:15] op_sel_hi:[1,0]
	v_pk_mul_f32 v[50:51], v[22:23], s[14:15] op_sel_hi:[1,0]
	v_pk_mul_f32 v[54:55], v[20:21], s[14:15] op_sel_hi:[1,0]
	v_pk_mul_f32 v[18:19], v[42:43], s[14:15] op_sel_hi:[1,0]
	v_pk_mul_f32 v[22:23], v[40:41], s[14:15] op_sel_hi:[1,0]
	v_pk_mul_f32 v[16:17], v[46:47], s[14:15] op_sel_hi:[1,0]
	v_pk_mul_f32 v[20:21], v[44:45], s[14:15] op_sel_hi:[1,0]
	v_pk_mul_f32 v[40:41], v[10:11], s[14:15] op_sel_hi:[1,0]
	v_pk_mul_f32 v[44:45], v[8:9], s[14:15] op_sel_hi:[1,0]
	v_pk_mul_f32 v[34:35], v[14:15], s[14:15] op_sel_hi:[1,0]
	v_pk_mul_f32 v[42:43], v[12:13], s[14:15] op_sel_hi:[1,0]
	v_pk_mul_f32 v[10:11], v[26:27], s[14:15] op_sel_hi:[1,0]
	v_pk_mul_f32 v[14:15], v[24:25], s[14:15] op_sel_hi:[1,0]
	v_pk_mul_f32 v[8:9], v[30:31], s[14:15] op_sel_hi:[1,0]
	v_pk_mul_f32 v[12:13], v[28:29], s[14:15] op_sel_hi:[1,0]
	v_pk_mul_f32 v[2:3], v[2:3], s[14:15] op_sel_hi:[1,0]
	v_pk_mul_f32 v[24:25], v[0:1], s[14:15] op_sel_hi:[1,0]
	v_pk_mul_f32 v[0:1], v[6:7], s[14:15] op_sel_hi:[1,0]
	v_pk_mul_f32 v[4:5], v[4:5], s[14:15] op_sel_hi:[1,0]
	s_and_b64 vcc, exec, s[12:13]
	s_cbranch_vccz .LBB0_575

; #define PG8_STAGE(bufoff, gbase, voff) do { _Pragma("unroll") for (int _i = 0; _i < 2; ++_i) \
;         __builtin_amdgcn_global_load_lds((const unsigned*)((const char*)(gbase) + (voff)[_i]), (LAS unsigned*)(lds + (bufoff) + ldsw + _i * 8192), 16, 0, 0); } while (0)
; #define PG8_LDA(dst, b, h) do { _Pragma("unroll") for (int m = 0; m < 4; ++m) _Pragma("unroll") for (int k = 0; k < 2; ++k) dst[m][k] = *(const LAS bf16x8*)(lds + PG8_SA(b, h) + aoff + m * 2048 + k * KOFF); } while (0)
; #define PG8_LDB(dst, b, h) do { _Pragma("unroll") for (int n = 0; n < 2; ++n) _Pragma("unroll") for (int k = 0; k < 2; ++k) dst[n][k] = *(const LAS bf16x8*)(lds + PG8_SB(b, h) + boff + n * 2048 + k * KOFF); } while (0)
; #define PG8_WAIT_V(n) asm volatile("s_waitcnt vmcnt(" #n ")" ::: "memory")
; #define PG8_WAIT_L(n) asm volatile("s_waitcnt lgkmcnt(" #n ")" ::: "memory")
; #define PG8_BAR __builtin_amdgcn_s_barrier()
; #define PG8_SCHED __builtin_amdgcn_sched_barrier(0)
; template <class Epi, bool ALIGN_EPI = true, bool FP8 = false>
; __device__ __forceinline__ void gemm_phase(LAS unsigned char* lds, const Gemm g, const StaticOrder& S, const Epi& E, const int wid) {
;     ...
;             const char* a1 = cA + (size_t)(t + 1) * kstep;
;             const char* a2 = last ? nA : cA + (size_t)(t + 2) * kstep; const char* b2 = last ? nB : cB + (size_t)(t + 2) * kstep;
;             const char* a3 = a2 + kstep; const char* b3 = b2 + kstep;
;             PG8_LDB(B0, 0, 0); PG8_LDB(B1, 0, 1); PG8_SCHED; PG8_LDA(At, 0, 0); PG8_STAGE(PG8_SA(1, 1), a1 + hstep, voffA);
;             PG8_WAIT_V(8); PG8_WAIT_L(0); PG8_BAR; PG8_MMA(0, 0, At, B0); PG8_MMA(0, 1, At, B1); PG8_BAR; PG8_SCHED;
;             PG8_LDA(At, 0, 1); PG8_STAGE(PG8_SB(0, 0), b2, voffB); PG8_STAGE(PG8_SB(0, 1), b2 + hstep, voffB); PG8_STAGE(PG8_SA(0, 0), a2, voffA);
;             PG8_WAIT_V(8); PG8_WAIT_L(0); PG8_BAR; PG8_MMA(1, 0, At, B0); PG8_MMA(1, 1, At, B1); PG8_BAR; PG8_SCHED;
.LBB0_2058:
	v_add_u32_e32 v128, s83, v192
	v_add_u32_e32 v132, s84, v192
	ds_read_b128 v[152:155], v128
	ds_read_b128 v[156:159], v128 offset:1024
	ds_read_b128 v[144:147], v128 offset:2048
	ds_read_b128 v[148:151], v128 offset:3072
	ds_read_b128 v[136:139], v132
	ds_read_b128 v[140:143], v132 offset:1024
	ds_read_b128 v[128:131], v132 offset:2048
	ds_read_b128 v[132:135], v132 offset:3072
	s_add_i32 s3, s42, 2
	s_add_u32 s43, s64, 0xfffe0080
	s_addc_u32 s52, s65, -1
	s_cmp_eq_u32 s35, s42
	s_cselect_b32 s69, s11, s52
	s_cselect_b32 s68, s16, s43
	s_cselect_b32 s67, s29, s90
	s_cselect_b32 s66, s31, s89
	v_lshl_add_u64 v[188:189], s[64:65], 0, v[174:175]
	s_add_i32 m0, s72, 0xc000
	ds_read_b128 v[180:183], v193
	ds_read_b128 v[184:187], v193 offset:1024
	ds_read_b128 v[196:199], v193 offset:2048
	ds_read_b128 v[200:203], v193 offset:3072
	ds_read_b128 v[204:207], v193 offset:4096
	ds_read_b128 v[208:211], v193 offset:5120
	ds_read_b128 v[212:215], v193 offset:6144
	ds_read_b128 v[216:219], v193 offset:7168
	global_load_lds_dwordx4 v[188:189], off
	v_lshl_add_u64 v[188:189], s[64:65], 0, v[176:177]
	s_add_i32 m0, s72, 0xe000
	s_nop 0
	global_load_lds_dwordx4 v[188:189], off
	s_setprio 1
	s_waitcnt vmcnt(8) lgkmcnt(0)
	s_barrier
	v_mfma_f32_16x16x128_f8f6f4 v[120:123], v[152:159], v[180:187], v[120:123]
	v_mfma_f32_16x16x128_f8f6f4 v[124:127], v[144:151], v[180:187], v[124:127]
	v_mfma_f32_16x16x128_f8f6f4 v[112:115], v[152:159], v[196:203], v[112:115]
	v_mfma_f32_16x16x128_f8f6f4 v[116:119], v[144:151], v[196:203], v[116:119]
	v_mfma_f32_16x16x128_f8f6f4 v[104:107], v[152:159], v[204:211], v[104:107]
	v_mfma_f32_16x16x128_f8f6f4 v[108:111], v[144:151], v[204:211], v[108:111]
	v_mfma_f32_16x16x128_f8f6f4 v[96:99], v[152:159], v[212:219], v[96:99]
	v_mfma_f32_16x16x128_f8f6f4 v[100:103], v[144:151], v[212:219], v[100:103]
	v_mfma_f32_16x16x128_f8f6f4 v[88:91], v[136:143], v[180:187], v[88:91]
	v_mfma_f32_16x16x128_f8f6f4 v[92:95], v[128:135], v[180:187], v[92:95]
	v_mfma_f32_16x16x128_f8f6f4 v[80:83], v[136:143], v[196:203], v[80:83]
	v_mfma_f32_16x16x128_f8f6f4 v[84:87], v[128:135], v[196:203], v[84:87]
	v_mfma_f32_16x16x128_f8f6f4 v[72:75], v[136:143], v[204:211], v[72:75]
	v_mfma_f32_16x16x128_f8f6f4 v[76:79], v[128:135], v[204:211], v[76:79]
	s_barrier
	v_mfma_f32_16x16x128_f8f6f4 v[64:67], v[136:143], v[212:219], v[64:67]
	v_mfma_f32_16x16x128_f8f6f4 v[68:71], v[128:135], v[212:219], v[68:71]
	s_setprio 0
	s_add_i32 s42, s83, s71
	v_lshl_add_u64 v[180:181], s[66:67], 0, v[162:163]
	s_mov_b32 m0, s42
	ds_read_b128 v[196:199], v193 offset:16384
	ds_read_b128 v[200:203], v193 offset:17408
	ds_read_b128 v[204:207], v193 offset:18432
	ds_read_b128 v[208:211], v193 offset:19456
	ds_read_b128 v[212:215], v193 offset:20480
	ds_read_b128 v[216:219], v193 offset:21504
	ds_read_b128 v[220:223], v193 offset:22528
	ds_read_b128 v[224:227], v193 offset:23552
	global_load_lds_dwordx4 v[180:181], off
	s_add_i32 m0, s42, 0x2000
	s_add_u32 s42, s66, 0x20000
	v_lshl_add_u64 v[182:183], s[66:67], 0, v[166:167]
	s_addc_u32 s43, s67, 0
	s_add_i32 s52, s84, s71
	global_load_lds_dwordx4 v[182:183], off
	v_lshl_add_u64 v[184:185], s[42:43], 0, v[162:163]
	s_mov_b32 m0, s52
	v_lshl_add_u64 v[186:187], s[68:69], 0, v[164:165]
	global_load_lds_dwordx4 v[184:185], off
	v_lshl_add_u64 v[184:185], s[42:43], 0, v[166:167]
	s_add_i32 m0, s52, 0x2000
	s_nop 0
	global_load_lds_dwordx4 v[184:185], off
	v_lshl_add_u64 v[184:185], s[68:69], 0, v[160:161]
	s_mov_b32 m0, s72
	s_nop 0
	global_load_lds_dwordx4 v[184:185], off
	s_mov_b32 m0, s73
	s_nop 0
	global_load_lds_dwordx4 v[186:187], off
	s_setprio 1
	s_waitcnt vmcnt(8) lgkmcnt(0)
	s_barrier
	v_mfma_f32_16x16x128_f8f6f4 v[56:59], v[152:159], v[196:203], v[56:59]
	v_mfma_f32_16x16x128_f8f6f4 v[60:63], v[144:151], v[196:203], v[60:63]
	v_mfma_f32_16x16x128_f8f6f4 v[48:51], v[152:159], v[204:211], v[48:51]
	v_mfma_f32_16x16x128_f8f6f4 v[52:55], v[144:151], v[204:211], v[52:55]
	v_mfma_f32_16x16x128_f8f6f4 v[40:43], v[152:159], v[212:219], v[40:43]
	v_mfma_f32_16x16x128_f8f6f4 v[44:47], v[144:151], v[212:219], v[44:47]
	v_mfma_f32_16x16x128_f8f6f4 v[188:191], v[152:159], v[220:227], v[32:35]
	v_mfma_f32_16x16x128_f8f6f4 v[228:231], v[144:151], v[220:227], v[36:39]
	v_mfma_f32_16x16x128_f8f6f4 v[232:235], v[136:143], v[196:203], v[24:27]
	v_mfma_f32_16x16x128_f8f6f4 v[236:239], v[128:135], v[196:203], v[28:31]
	v_mfma_f32_16x16x128_f8f6f4 v[240:243], v[136:143], v[204:211], v[16:19]
	v_mfma_f32_16x16x128_f8f6f4 v[204:207], v[128:135], v[204:211], v[20:23]
	v_mfma_f32_16x16x128_f8f6f4 v[208:211], v[136:143], v[212:219], v[8:11]
	v_mfma_f32_16x16x128_f8f6f4 v[212:215], v[128:135], v[212:219], v[12:15]
	s_barrier
; #define PG8_STAGE(bufoff, gbase, voff) do { _Pragma("unroll") for (int _i = 0; _i < 2; ++_i) \
;         __builtin_amdgcn_global_load_lds((const unsigned*)((const char*)(gbase) + (voff)[_i]), (LAS unsigned*)(lds + (bufoff) + ldsw + _i * 8192), 16, 0, 0); } while (0)
; #define PG8_LDA(dst, b, h) do { _Pragma("unroll") for (int m = 0; m < 4; ++m) _Pragma("unroll") for (int k = 0; k < 2; ++k) dst[m][k] = *(const LAS bf16x8*)(lds + PG8_SA(b, h) + aoff + m * 2048 + k * KOFF); } while (0)
; #define PG8_LDB(dst, b, h) do { _Pragma("unroll") for (int n = 0; n < 2; ++n) _Pragma("unroll") for (int k = 0; k < 2; ++k) dst[n][k] = *(const LAS bf16x8*)(lds + PG8_SB(b, h) + boff + n * 2048 + k * KOFF); } while (0)
; #define PG8_WAIT_V(n) asm volatile("s_waitcnt vmcnt(" #n ")" ::: "memory")
; #define PG8_WAIT_L(n) asm volatile("s_waitcnt lgkmcnt(" #n ")" ::: "memory")
; #define PG8_BAR __builtin_amdgcn_s_barrier()
; #define PG8_SCHED __builtin_amdgcn_sched_barrier(0)
; template <class Epi, bool ALIGN_EPI = true, bool FP8 = false>
; __device__ __forceinline__ void gemm_phase(LAS unsigned char* lds, const Gemm g, const StaticOrder& S, const Epi& E, const int wid) {
;     ...
;             PG8_WAIT_V(8); PG8_WAIT_L(0); PG8_BAR; PG8_MMA(1, 0, At, B0); PG8_MMA(1, 1, At, B1); PG8_BAR; PG8_SCHED;
;             PG8_LDB(B0, 1, 0); PG8_LDB(B1, 1, 1); PG8_SCHED; PG8_LDA(At, 1, 0); PG8_STAGE(PG8_SA(0, 1), a2 + hstep, voffA);
;             PG8_WAIT_V(8); PG8_WAIT_L(0); PG8_BAR; PG8_MMA(0, 0, At, B0); PG8_MMA(0, 1, At, B1); PG8_BAR; PG8_SCHED;
;             PG8_LDA(At, 1, 1); PG8_STAGE(PG8_SB(1, 0), b3, voffB); PG8_STAGE(PG8_SB(1, 1), b3 + hstep, voffB); PG8_STAGE(PG8_SA(1, 0), a3, voffA);
;             PG8_WAIT_V(8); PG8_WAIT_L(0); PG8_BAR; PG8_MMA(1, 0, At, B0); PG8_MMA(1, 1, At, B1); PG8_BAR; PG8_SCHED;
;         }
	v_mfma_f32_16x16x128_f8f6f4 v[216:219], v[136:143], v[220:227], v[0:3]
	v_mfma_f32_16x16x128_f8f6f4 v[220:223], v[128:135], v[220:227], v[4:7]
	s_setprio 0
	s_add_i32 s52, 0, 0x18000
	s_add_i32 s54, 0, 0x1c000
	s_nop 0
	v_add_u32_e32 v12, s52, v192
	v_add_u32_e32 v16, s54, v192
	ds_read_b128 v[0:3], v12
	ds_read_b128 v[4:7], v12 offset:1024
	ds_read_b128 v[8:11], v12 offset:2048
	ds_read_b128 v[12:15], v12 offset:3072
	ds_read_b128 v[128:131], v16
	ds_read_b128 v[132:135], v16 offset:1024
	ds_read_b128 v[136:139], v16 offset:2048
	ds_read_b128 v[140:143], v16 offset:3072
	s_add_u32 s42, s68, 0x20000
	s_addc_u32 s43, s69, 0
	s_mov_b32 m0, s74
	v_lshl_add_u64 v[152:153], s[42:43], 0, v[160:161]
	ds_read_b128 v[16:19], v193 offset:32768
	ds_read_b128 v[20:23], v193 offset:33792
	ds_read_b128 v[24:27], v193 offset:34816
	ds_read_b128 v[28:31], v193 offset:35840
	ds_read_b128 v[32:35], v193 offset:36864
	ds_read_b128 v[36:39], v193 offset:37888
	ds_read_b128 v[144:147], v193 offset:38912
	ds_read_b128 v[148:151], v193 offset:39936
	global_load_lds_dwordx4 v[152:153], off
	v_lshl_add_u64 v[152:153], s[42:43], 0, v[164:165]
	s_mov_b32 m0, s75
	s_nop 0
	global_load_lds_dwordx4 v[152:153], off
	s_setprio 1
	s_waitcnt vmcnt(8) lgkmcnt(0)
	s_barrier
	v_mfma_f32_16x16x128_f8f6f4 v[120:123], v[0:7], v[16:23], v[120:123]
	v_mfma_f32_16x16x128_f8f6f4 v[124:127], v[8:15], v[16:23], v[124:127]
	v_mfma_f32_16x16x128_f8f6f4 v[112:115], v[0:7], v[24:31], v[112:115]
	v_mfma_f32_16x16x128_f8f6f4 v[116:119], v[8:15], v[24:31], v[116:119]
	v_mfma_f32_16x16x128_f8f6f4 v[104:107], v[0:7], v[32:39], v[104:107]
	v_mfma_f32_16x16x128_f8f6f4 v[108:111], v[8:15], v[32:39], v[108:111]
	v_mfma_f32_16x16x128_f8f6f4 v[96:99], v[0:7], v[144:151], v[96:99]
	v_mfma_f32_16x16x128_f8f6f4 v[100:103], v[8:15], v[144:151], v[100:103]
	v_mfma_f32_16x16x128_f8f6f4 v[88:91], v[128:135], v[16:23], v[88:91]
	v_mfma_f32_16x16x128_f8f6f4 v[92:95], v[136:143], v[16:23], v[92:95]
	v_mfma_f32_16x16x128_f8f6f4 v[80:83], v[128:135], v[24:31], v[80:83]
	v_mfma_f32_16x16x128_f8f6f4 v[84:87], v[136:143], v[24:31], v[84:87]
	v_mfma_f32_16x16x128_f8f6f4 v[72:75], v[128:135], v[32:39], v[72:75]
	v_mfma_f32_16x16x128_f8f6f4 v[76:79], v[136:143], v[32:39], v[76:79]
	s_barrier
	v_mfma_f32_16x16x128_f8f6f4 v[64:67], v[128:135], v[144:151], v[64:67]
	v_mfma_f32_16x16x128_f8f6f4 v[68:71], v[136:143], v[144:151], v[68:71]
	s_setprio 0
	s_add_i32 s42, s52, s71
	v_lshl_add_u64 v[24:25], v[180:181], 0, s[20:21]
	s_mov_b32 m0, s42
	ds_read_b128 v[16:19], v193 offset:49152
	ds_read_b128 v[20:23], v193 offset:50176
	ds_read_b128 v[144:147], v193 offset:51200
	ds_read_b128 v[148:151], v193 offset:52224
	ds_read_b128 v[152:155], v193 offset:53248
	ds_read_b128 v[156:159], v193 offset:54272
	ds_read_b128 v[196:199], v193 offset:55296
	ds_read_b128 v[200:203], v193 offset:56320
	global_load_lds_dwordx4 v[24:25], off
	s_add_i32 m0, s42, 0x2000
	s_add_u32 s42, s66, 0x20080
	v_lshl_add_u64 v[24:25], v[182:183], 0, s[20:21]
	s_addc_u32 s43, s67, 0
	s_add_i32 s52, s54, s71
	global_load_lds_dwordx4 v[24:25], off
	v_lshl_add_u64 v[24:25], s[42:43], 0, v[162:163]
	s_mov_b32 m0, s52
	s_nop 0
	global_load_lds_dwordx4 v[24:25], off
	v_lshl_add_u64 v[24:25], s[42:43], 0, v[166:167]
	s_add_i32 m0, s52, 0x2000
	s_nop 0
	global_load_lds_dwordx4 v[24:25], off
	v_lshl_add_u64 v[24:25], v[184:185], 0, s[20:21]
	s_mov_b32 m0, s80
	s_nop 0
	global_load_lds_dwordx4 v[24:25], off
	v_lshl_add_u64 v[24:25], v[186:187], 0, s[20:21]
	s_mov_b32 m0, s81
	s_nop 0
	global_load_lds_dwordx4 v[24:25], off
	s_setprio 1
	s_waitcnt vmcnt(8) lgkmcnt(0)
	s_barrier
	v_mfma_f32_16x16x128_f8f6f4 v[56:59], v[0:7], v[16:23], v[56:59]
	v_mfma_f32_16x16x128_f8f6f4 v[60:63], v[8:15], v[16:23], v[60:63]
	v_mfma_f32_16x16x128_f8f6f4 v[48:51], v[0:7], v[144:151], v[48:51]
	v_mfma_f32_16x16x128_f8f6f4 v[52:55], v[8:15], v[144:151], v[52:55]
	v_mfma_f32_16x16x128_f8f6f4 v[40:43], v[0:7], v[152:159], v[40:43]
	v_mfma_f32_16x16x128_f8f6f4 v[44:47], v[8:15], v[152:159], v[44:47]
	v_mfma_f32_16x16x128_f8f6f4 v[32:35], v[0:7], v[196:203], v[188:191]
	v_mfma_f32_16x16x128_f8f6f4 v[36:39], v[8:15], v[196:203], v[228:231]
	v_mfma_f32_16x16x128_f8f6f4 v[24:27], v[128:135], v[16:23], v[232:235]
	v_mfma_f32_16x16x128_f8f6f4 v[28:31], v[136:143], v[16:23], v[236:239]
	v_mfma_f32_16x16x128_f8f6f4 v[16:19], v[128:135], v[144:151], v[240:243]
	v_mfma_f32_16x16x128_f8f6f4 v[20:23], v[136:143], v[144:151], v[204:207]
	v_mfma_f32_16x16x128_f8f6f4 v[8:11], v[128:135], v[152:159], v[208:211]
	v_mfma_f32_16x16x128_f8f6f4 v[12:15], v[136:143], v[152:159], v[212:215]
	s_barrier
	v_mfma_f32_16x16x128_f8f6f4 v[0:3], v[128:135], v[196:203], v[216:219]
	v_mfma_f32_16x16x128_f8f6f4 v[4:7], v[136:143], v[196:203], v[220:223]
	s_setprio 0
	s_add_u32 s64, s64, 0x100
	s_addc_u32 s65, s65, 0
	s_add_u32 s89, s89, 0x100
	s_addc_u32 s90, s90, 0
	s_cmp_ge_u32 s3, s9
	s_mov_b32 s42, s3
	s_cbranch_scc0 .LBB0_2058
	s_and_b64 vcc, exec, s[22:23]
	s_cbranch_vccz .LBB0_2061
	s_barrier

; #define PG8_STAGE(bufoff, gbase, voff) do { _Pragma("unroll") for (int _i = 0; _i < 2; ++_i) \
;         __builtin_amdgcn_global_load_lds((const unsigned*)((const char*)(gbase) + (voff)[_i]), (LAS unsigned*)(lds + (bufoff) + ldsw + _i * 8192), 16, 0, 0); } while (0)
; #define PG8_LDA(dst, b, h) do { _Pragma("unroll") for (int m = 0; m < 4; ++m) _Pragma("unroll") for (int k = 0; k < 2; ++k) dst[m][k] = *(const LAS bf16x8*)(lds + PG8_SA(b, h) + aoff + m * 2048 + k * KOFF); } while (0)
; #define PG8_LDB(dst, b, h) do { _Pragma("unroll") for (int n = 0; n < 2; ++n) _Pragma("unroll") for (int k = 0; k < 2; ++k) dst[n][k] = *(const LAS bf16x8*)(lds + PG8_SB(b, h) + boff + n * 2048 + k * KOFF); } while (0)
; #define PG8_WAIT_V(n) asm volatile("s_waitcnt vmcnt(" #n ")" ::: "memory")
; #define PG8_WAIT_L(n) asm volatile("s_waitcnt lgkmcnt(" #n ")" ::: "memory")
; #define PG8_BAR __builtin_amdgcn_s_barrier()
; #define PG8_SCHED __builtin_amdgcn_sched_barrier(0)
; template <class Epi, bool ALIGN_EPI = true, bool FP8 = false>
; __device__ __forceinline__ void gemm_phase(LAS unsigned char* lds, const Gemm g, const StaticOrder& S, const Epi& E, const int wid) {
;     ...
;             const char* a1 = cA + (size_t)(t + 1) * kstep;
;             const char* a2 = last ? nA : cA + (size_t)(t + 2) * kstep; const char* b2 = last ? nB : cB + (size_t)(t + 2) * kstep;
;             const char* a3 = a2 + kstep; const char* b3 = b2 + kstep;
;             PG8_LDB(B0, 0, 0); PG8_LDB(B1, 0, 1); PG8_SCHED; PG8_LDA(At, 0, 0); PG8_STAGE(PG8_SA(1, 1), a1 + hstep, voffA);
;             PG8_WAIT_V(8); PG8_WAIT_L(0); PG8_BAR; PG8_MMA(0, 0, At, B0); PG8_MMA(0, 1, At, B1); PG8_BAR; PG8_SCHED;
;             PG8_LDA(At, 0, 1); PG8_STAGE(PG8_SB(0, 0), b2, voffB); PG8_STAGE(PG8_SB(0, 1), b2 + hstep, voffB); PG8_STAGE(PG8_SA(0, 0), a2, voffA);
;             PG8_WAIT_V(8); PG8_WAIT_L(0); PG8_BAR; PG8_MMA(1, 0, At, B0); PG8_MMA(1, 1, At, B1); PG8_BAR; PG8_SCHED;
.LBB0_2290:
	ds_read_b128 v[152:155], v218
	ds_read_b128 v[156:159], v218 offset:1024
	ds_read_b128 v[144:147], v218 offset:2048
	ds_read_b128 v[148:151], v218 offset:3072
	ds_read_b128 v[136:139], v219
	ds_read_b128 v[140:143], v219 offset:1024
	ds_read_b128 v[128:131], v219 offset:2048
	ds_read_b128 v[132:135], v219 offset:3072
	s_add_i32 s3, s38, 2
	s_add_u32 s36, s34, 0xfffc0080
	s_addc_u32 s37, s35, -1
	s_cmp_eq_u32 s88, s38
	s_cselect_b32 s38, s31, s36
	s_cselect_b32 s39, s21, s37
	s_cselect_b32 s37, s19, s90
	s_cselect_b32 s36, s87, s89
	v_lshl_add_u64 v[212:213], s[34:35], 0, v[198:199]
	s_add_i32 m0, s27, 0xc000
	ds_read_b128 v[160:163], v220
	ds_read_b128 v[164:167], v220 offset:1024
	ds_read_b128 v[168:171], v220 offset:2048
	ds_read_b128 v[172:175], v220 offset:3072
	ds_read_b128 v[176:179], v220 offset:4096
	ds_read_b128 v[180:183], v220 offset:5120
	ds_read_b128 v[204:207], v220 offset:6144
	ds_read_b128 v[208:211], v220 offset:7168
	global_load_lds_dwordx4 v[212:213], off
	v_lshl_add_u64 v[212:213], s[34:35], 0, v[200:201]
	s_add_i32 m0, s27, 0xe000
	s_nop 0
	global_load_lds_dwordx4 v[212:213], off
	s_setprio 1
	s_waitcnt vmcnt(8) lgkmcnt(0)
	s_barrier
	v_mfma_f32_16x16x128_f8f6f4 v[120:123], v[152:159], v[160:167], v[120:123]
	v_mfma_f32_16x16x128_f8f6f4 v[124:127], v[144:151], v[160:167], v[124:127]
	v_mfma_f32_16x16x128_f8f6f4 v[104:107], v[152:159], v[168:175], v[104:107]
	v_mfma_f32_16x16x128_f8f6f4 v[108:111], v[144:151], v[168:175], v[108:111]
	v_mfma_f32_16x16x128_f8f6f4 v[96:99], v[152:159], v[176:183], v[96:99]
	v_mfma_f32_16x16x128_f8f6f4 v[100:103], v[144:151], v[176:183], v[100:103]
	v_mfma_f32_16x16x128_f8f6f4 v[80:83], v[152:159], v[204:211], v[80:83]
	v_mfma_f32_16x16x128_f8f6f4 v[84:87], v[144:151], v[204:211], v[84:87]
	v_mfma_f32_16x16x128_f8f6f4 v[112:115], v[136:143], v[160:167], v[112:115]
	v_mfma_f32_16x16x128_f8f6f4 v[116:119], v[128:135], v[160:167], v[116:119]
	v_mfma_f32_16x16x128_f8f6f4 v[88:91], v[136:143], v[168:175], v[88:91]
	v_mfma_f32_16x16x128_f8f6f4 v[92:95], v[128:135], v[168:175], v[92:95]
	v_mfma_f32_16x16x128_f8f6f4 v[72:75], v[136:143], v[176:183], v[72:75]
	v_mfma_f32_16x16x128_f8f6f4 v[76:79], v[128:135], v[176:183], v[76:79]
	s_barrier
	v_mfma_f32_16x16x128_f8f6f4 v[64:67], v[136:143], v[204:211], v[64:67]
	v_mfma_f32_16x16x128_f8f6f4 v[68:71], v[128:135], v[204:211], v[68:71]
	s_setprio 0
	s_add_i32 s42, s75, s53
	v_lshl_add_u64 v[160:161], s[36:37], 0, v[188:189]
	s_mov_b32 m0, s42
	ds_read_b128 v[168:171], v220 offset:16384
	ds_read_b128 v[172:175], v220 offset:17408
	ds_read_b128 v[176:179], v220 offset:18432
	ds_read_b128 v[180:183], v220 offset:19456
	ds_read_b128 v[204:207], v220 offset:20480
	ds_read_b128 v[208:211], v220 offset:21504
	ds_read_b128 v[222:225], v220 offset:22528
	ds_read_b128 v[226:229], v220 offset:23552
	global_load_lds_dwordx4 v[160:161], off
	s_add_i32 m0, s42, 0x2000
	s_add_u32 s42, s36, 0x40000
	v_lshl_add_u64 v[162:163], s[36:37], 0, v[184:185]
	s_addc_u32 s43, s37, 0
	s_add_i32 s52, s76, s53
	global_load_lds_dwordx4 v[162:163], off
	v_lshl_add_u64 v[164:165], s[42:43], 0, v[188:189]
	s_mov_b32 m0, s52
	v_lshl_add_u64 v[166:167], s[38:39], 0, v[186:187]
	global_load_lds_dwordx4 v[164:165], off
	v_lshl_add_u64 v[164:165], s[42:43], 0, v[184:185]
	s_add_i32 m0, s52, 0x2000
	s_nop 0
	global_load_lds_dwordx4 v[164:165], off
	v_lshl_add_u64 v[164:165], s[38:39], 0, v[190:191]
	s_mov_b32 m0, s27
	s_nop 0
	global_load_lds_dwordx4 v[164:165], off
	s_mov_b32 m0, s55
	s_nop 0
	global_load_lds_dwordx4 v[166:167], off
	s_setprio 1
	s_waitcnt vmcnt(8) lgkmcnt(0)
	s_barrier
	v_mfma_f32_16x16x128_f8f6f4 v[56:59], v[152:159], v[168:175], v[56:59]
	v_mfma_f32_16x16x128_f8f6f4 v[60:63], v[144:151], v[168:175], v[60:63]
	v_mfma_f32_16x16x128_f8f6f4 v[48:51], v[152:159], v[176:183], v[48:51]
	v_mfma_f32_16x16x128_f8f6f4 v[52:55], v[144:151], v[176:183], v[52:55]
	v_mfma_f32_16x16x128_f8f6f4 v[32:35], v[152:159], v[204:211], v[32:35]
	v_mfma_f32_16x16x128_f8f6f4 v[212:215], v[144:151], v[204:211], v[36:39]
	v_mfma_f32_16x16x128_f8f6f4 v[230:233], v[152:159], v[222:229], v[16:19]
	v_mfma_f32_16x16x128_f8f6f4 v[234:237], v[144:151], v[222:229], v[20:23]
	v_mfma_f32_16x16x128_f8f6f4 v[44:47], v[128:135], v[168:175], v[44:47]
	v_mfma_f32_16x16x128_f8f6f4 v[238:241], v[136:143], v[168:175], v[40:43]
	v_mfma_f32_16x16x128_f8f6f4 v[242:245], v[136:143], v[176:183], v[24:27]
	v_mfma_f32_16x16x128_f8f6f4 v[176:179], v[128:135], v[176:183], v[28:31]
	v_mfma_f32_16x16x128_f8f6f4 v[180:183], v[136:143], v[204:211], v[8:11]
	v_mfma_f32_16x16x128_f8f6f4 v[204:207], v[128:135], v[204:211], v[12:15]
	s_barrier
; #define PG8_STAGE(bufoff, gbase, voff) do { _Pragma("unroll") for (int _i = 0; _i < 2; ++_i) \
;         __builtin_amdgcn_global_load_lds((const unsigned*)((const char*)(gbase) + (voff)[_i]), (LAS unsigned*)(lds + (bufoff) + ldsw + _i * 8192), 16, 0, 0); } while (0)
; #define PG8_LDA(dst, b, h) do { _Pragma("unroll") for (int m = 0; m < 4; ++m) _Pragma("unroll") for (int k = 0; k < 2; ++k) dst[m][k] = *(const LAS bf16x8*)(lds + PG8_SA(b, h) + aoff + m * 2048 + k * KOFF); } while (0)
; #define PG8_LDB(dst, b, h) do { _Pragma("unroll") for (int n = 0; n < 2; ++n) _Pragma("unroll") for (int k = 0; k < 2; ++k) dst[n][k] = *(const LAS bf16x8*)(lds + PG8_SB(b, h) + boff + n * 2048 + k * KOFF); } while (0)
; #define PG8_WAIT_V(n) asm volatile("s_waitcnt vmcnt(" #n ")" ::: "memory")
; #define PG8_WAIT_L(n) asm volatile("s_waitcnt lgkmcnt(" #n ")" ::: "memory")
; #define PG8_BAR __builtin_amdgcn_s_barrier()
; #define PG8_SCHED __builtin_amdgcn_sched_barrier(0)
; template <class Epi, bool ALIGN_EPI = true, bool FP8 = false>
; __device__ __forceinline__ void gemm_phase(LAS unsigned char* lds, const Gemm g, const StaticOrder& S, const Epi& E, const int wid) {
;     ...
;             PG8_WAIT_V(8); PG8_WAIT_L(0); PG8_BAR; PG8_MMA(1, 0, At, B0); PG8_MMA(1, 1, At, B1); PG8_BAR; PG8_SCHED;
;             PG8_LDB(B0, 1, 0); PG8_LDB(B1, 1, 1); PG8_SCHED; PG8_LDA(At, 1, 0); PG8_STAGE(PG8_SA(0, 1), a2 + hstep, voffA);
;             PG8_WAIT_V(8); PG8_WAIT_L(0); PG8_BAR; PG8_MMA(0, 0, At, B0); PG8_MMA(0, 1, At, B1); PG8_BAR; PG8_SCHED;
;             PG8_LDA(At, 1, 1); PG8_STAGE(PG8_SB(1, 0), b3, voffB); PG8_STAGE(PG8_SB(1, 1), b3 + hstep, voffB); PG8_STAGE(PG8_SA(1, 0), a3, voffA);
;             PG8_WAIT_V(8); PG8_WAIT_L(0); PG8_BAR; PG8_MMA(1, 0, At, B0); PG8_MMA(1, 1, At, B1); PG8_BAR; PG8_SCHED;
;         }
	v_mfma_f32_16x16x128_f8f6f4 v[208:211], v[136:143], v[222:229], v[0:3]
	v_mfma_f32_16x16x128_f8f6f4 v[222:225], v[128:135], v[222:229], v[4:7]
	s_setprio 0
	s_add_i32 s42, 0, 0x18000
	s_add_i32 s43, 0, 0x1c000
	s_nop 0
	v_add_u32_e32 v12, s42, v217
	v_add_u32_e32 v16, s43, v217
	ds_read_b128 v[0:3], v12
	ds_read_b128 v[4:7], v12 offset:1024
	ds_read_b128 v[8:11], v12 offset:2048
	ds_read_b128 v[12:15], v12 offset:3072
	ds_read_b128 v[128:131], v16
	ds_read_b128 v[132:135], v16 offset:1024
	ds_read_b128 v[136:139], v16 offset:2048
	ds_read_b128 v[140:143], v16 offset:3072
	s_add_u32 s38, s38, 0x40000
	s_addc_u32 s39, s39, 0
	s_mov_b32 m0, s64
	v_lshl_add_u64 v[152:153], s[38:39], 0, v[190:191]
	ds_read_b128 v[16:19], v220 offset:32768
	ds_read_b128 v[20:23], v220 offset:33792
	ds_read_b128 v[24:27], v220 offset:34816
	ds_read_b128 v[28:31], v220 offset:35840
	ds_read_b128 v[36:39], v220 offset:36864
	ds_read_b128 v[40:43], v220 offset:37888
	ds_read_b128 v[144:147], v220 offset:38912
	ds_read_b128 v[148:151], v220 offset:39936
	global_load_lds_dwordx4 v[152:153], off
	v_lshl_add_u64 v[152:153], s[38:39], 0, v[186:187]
	s_mov_b32 m0, s65
	s_nop 0
	global_load_lds_dwordx4 v[152:153], off
	s_setprio 1
	s_waitcnt vmcnt(8) lgkmcnt(0)
	s_barrier
	v_mfma_f32_16x16x128_f8f6f4 v[120:123], v[0:7], v[16:23], v[120:123]
	v_mfma_f32_16x16x128_f8f6f4 v[124:127], v[8:15], v[16:23], v[124:127]
	v_mfma_f32_16x16x128_f8f6f4 v[104:107], v[0:7], v[24:31], v[104:107]
	v_mfma_f32_16x16x128_f8f6f4 v[108:111], v[8:15], v[24:31], v[108:111]
	v_mfma_f32_16x16x128_f8f6f4 v[96:99], v[0:7], v[36:43], v[96:99]
	v_mfma_f32_16x16x128_f8f6f4 v[100:103], v[8:15], v[36:43], v[100:103]
	v_mfma_f32_16x16x128_f8f6f4 v[80:83], v[0:7], v[144:151], v[80:83]
	v_mfma_f32_16x16x128_f8f6f4 v[84:87], v[8:15], v[144:151], v[84:87]
	v_mfma_f32_16x16x128_f8f6f4 v[112:115], v[128:135], v[16:23], v[112:115]
	v_mfma_f32_16x16x128_f8f6f4 v[116:119], v[136:143], v[16:23], v[116:119]
	v_mfma_f32_16x16x128_f8f6f4 v[88:91], v[128:135], v[24:31], v[88:91]
	v_mfma_f32_16x16x128_f8f6f4 v[92:95], v[136:143], v[24:31], v[92:95]
	v_mfma_f32_16x16x128_f8f6f4 v[72:75], v[128:135], v[36:43], v[72:75]
	v_mfma_f32_16x16x128_f8f6f4 v[76:79], v[136:143], v[36:43], v[76:79]
	s_barrier
	v_mfma_f32_16x16x128_f8f6f4 v[64:67], v[128:135], v[144:151], v[64:67]
	v_mfma_f32_16x16x128_f8f6f4 v[68:71], v[136:143], v[144:151], v[68:71]
	s_setprio 0
	s_add_i32 s38, s42, s53
	v_lshl_add_u64 v[16:17], v[160:161], 0, s[14:15]
	s_mov_b32 m0, s38
	ds_read_b128 v[24:27], v220 offset:49152
	ds_read_b128 v[28:31], v220 offset:50176
	ds_read_b128 v[144:147], v220 offset:51200
	ds_read_b128 v[148:151], v220 offset:52224
	ds_read_b128 v[152:155], v220 offset:53248
	ds_read_b128 v[156:159], v220 offset:54272
	ds_read_b128 v[168:171], v220 offset:55296
	ds_read_b128 v[172:175], v220 offset:56320
	global_load_lds_dwordx4 v[16:17], off
	s_add_i32 m0, s38, 0x2000
	s_add_u32 s36, s36, 0x40080
	v_lshl_add_u64 v[16:17], v[162:163], 0, s[14:15]
	s_addc_u32 s37, s37, 0
	s_add_i32 s38, s43, s53
	global_load_lds_dwordx4 v[16:17], off
	v_lshl_add_u64 v[16:17], s[36:37], 0, v[188:189]
	s_mov_b32 m0, s38
	s_nop 0
	global_load_lds_dwordx4 v[16:17], off
	v_lshl_add_u64 v[16:17], s[36:37], 0, v[184:185]
	s_add_i32 m0, s38, 0x2000
	s_nop 0
	global_load_lds_dwordx4 v[16:17], off
	v_lshl_add_u64 v[16:17], v[164:165], 0, s[14:15]
	s_mov_b32 m0, s71
	s_nop 0
	global_load_lds_dwordx4 v[16:17], off
	v_lshl_add_u64 v[16:17], v[166:167], 0, s[14:15]
	s_mov_b32 m0, s72
	s_nop 0
	global_load_lds_dwordx4 v[16:17], off
	s_setprio 1
	s_waitcnt vmcnt(8) lgkmcnt(0)
	s_barrier
	v_mfma_f32_16x16x128_f8f6f4 v[56:59], v[0:7], v[24:31], v[56:59]
	v_mfma_f32_16x16x128_f8f6f4 v[60:63], v[8:15], v[24:31], v[60:63]
	v_mfma_f32_16x16x128_f8f6f4 v[48:51], v[0:7], v[144:151], v[48:51]
	v_mfma_f32_16x16x128_f8f6f4 v[52:55], v[8:15], v[144:151], v[52:55]
	v_mfma_f32_16x16x128_f8f6f4 v[32:35], v[0:7], v[152:159], v[32:35]
	v_mfma_f32_16x16x128_f8f6f4 v[36:39], v[8:15], v[152:159], v[212:215]
	v_mfma_f32_16x16x128_f8f6f4 v[16:19], v[0:7], v[168:175], v[230:233]
	v_mfma_f32_16x16x128_f8f6f4 v[20:23], v[8:15], v[168:175], v[234:237]
	v_mfma_f32_16x16x128_f8f6f4 v[40:43], v[128:135], v[24:31], v[238:241]
	v_mfma_f32_16x16x128_f8f6f4 v[44:47], v[136:143], v[24:31], v[44:47]
	v_mfma_f32_16x16x128_f8f6f4 v[24:27], v[128:135], v[144:151], v[242:245]
	v_mfma_f32_16x16x128_f8f6f4 v[28:31], v[136:143], v[144:151], v[176:179]
	v_mfma_f32_16x16x128_f8f6f4 v[8:11], v[128:135], v[152:159], v[180:183]
	v_mfma_f32_16x16x128_f8f6f4 v[12:15], v[136:143], v[152:159], v[204:207]
	s_barrier
	v_mfma_f32_16x16x128_f8f6f4 v[0:3], v[128:135], v[168:175], v[208:211]
	v_mfma_f32_16x16x128_f8f6f4 v[4:7], v[136:143], v[168:175], v[222:225]
	s_setprio 0
	s_add_u32 s34, s34, 0x100
	s_addc_u32 s35, s35, 0
	s_add_u32 s89, s89, 0x100
	s_addc_u32 s90, s90, 0
	s_cmp_ge_u32 s3, s29
	s_mov_b32 s38, s3
	s_cbranch_scc0 .LBB0_2290
	s_and_b64 vcc, exec, s[12:13]
	s_cbranch_vccz .LBB0_2293
	s_barrier

; #define PG8_STAGE(bufoff, gbase, voff) do { _Pragma("unroll") for (int _i = 0; _i < 2; ++_i) \
;         __builtin_amdgcn_global_load_lds((const unsigned*)((const char*)(gbase) + (voff)[_i]), (LAS unsigned*)(lds + (bufoff) + ldsw + _i * 8192), 16, 0, 0); } while (0)
; #define PG8_LDA(dst, b, h) do { _Pragma("unroll") for (int m = 0; m < 4; ++m) _Pragma("unroll") for (int k = 0; k < 2; ++k) dst[m][k] = *(const LAS bf16x8*)(lds + PG8_SA(b, h) + aoff + m * 2048 + k * KOFF); } while (0)
; #define PG8_LDB(dst, b, h) do { _Pragma("unroll") for (int n = 0; n < 2; ++n) _Pragma("unroll") for (int k = 0; k < 2; ++k) dst[n][k] = *(const LAS bf16x8*)(lds + PG8_SB(b, h) + boff + n * 2048 + k * KOFF); } while (0)
; #define PG8_WAIT_V(n) asm volatile("s_waitcnt vmcnt(" #n ")" ::: "memory")
; #define PG8_WAIT_L(n) asm volatile("s_waitcnt lgkmcnt(" #n ")" ::: "memory")
; #define PG8_BAR __builtin_amdgcn_s_barrier()
; #define PG8_SCHED __builtin_amdgcn_sched_barrier(0)
; template <class Epi, bool ALIGN_EPI = true, bool FP8 = false>
; __device__ __forceinline__ void gemm_phase(LAS unsigned char* lds, const Gemm g, const StaticOrder& S, const Epi& E, const int wid) {
;     ...
;             const char* a1 = cA + (size_t)(t + 1) * kstep;
;             const char* a2 = last ? nA : cA + (size_t)(t + 2) * kstep; const char* b2 = last ? nB : cB + (size_t)(t + 2) * kstep;
;             const char* a3 = a2 + kstep; const char* b3 = b2 + kstep;
;             PG8_LDB(B0, 0, 0); PG8_LDB(B1, 0, 1); PG8_SCHED; PG8_LDA(At, 0, 0); PG8_STAGE(PG8_SA(1, 1), a1 + hstep, voffA);
;             PG8_WAIT_V(8); PG8_WAIT_L(0); PG8_BAR; PG8_MMA(0, 0, At, B0); PG8_MMA(0, 1, At, B1); PG8_BAR; PG8_SCHED;
;             PG8_LDA(At, 0, 1); PG8_STAGE(PG8_SB(0, 0), b2, voffB); PG8_STAGE(PG8_SB(0, 1), b2 + hstep, voffB); PG8_STAGE(PG8_SA(0, 0), a2, voffA);
;             PG8_WAIT_V(8); PG8_WAIT_L(0); PG8_BAR; PG8_MMA(1, 0, At, B0); PG8_MMA(1, 1, At, B1); PG8_BAR; PG8_SCHED;
.LBB0_2452:
	ds_read_b128 v[152:155], v148
	ds_read_b128 v[156:159], v148 offset:1024
	ds_read_b128 v[160:163], v148 offset:2048
	ds_read_b128 v[164:167], v148 offset:3072
	ds_read_b128 v[168:171], v149
	ds_read_b128 v[172:175], v149 offset:1024
	ds_read_b128 v[176:179], v149 offset:2048
	ds_read_b128 v[180:183], v149 offset:3072
	s_add_i32 s76, s30, 2
	s_add_u32 s31, s28, 0xfff80080
	s_addc_u32 s34, s29, -1
	s_cmp_eq_u32 s43, s30
	s_cselect_b32 s30, s42, s52
	s_cselect_b32 s35, s3, s34
	s_cselect_b32 s34, s17, s31
	s_cselect_b32 s31, s19, s75
	v_lshl_add_u64 v[144:145], s[28:29], 0, v[138:139]
	s_add_i32 m0, s25, 0xc000
	ds_read_b128 v[184:187], v150
	ds_read_b128 v[188:191], v150 offset:1024
	ds_read_b128 v[192:195], v150 offset:2048
	ds_read_b128 v[196:199], v150 offset:3072
	ds_read_b128 v[200:203], v150 offset:4096
	ds_read_b128 v[204:207], v150 offset:5120
	ds_read_b128 v[208:211], v150 offset:6144
	ds_read_b128 v[212:215], v150 offset:7168
	global_load_lds_dwordx4 v[144:145], off
	v_lshl_add_u64 v[144:145], s[28:29], 0, v[140:141]
	s_add_i32 m0, s25, 0xe000
	s_nop 0
	global_load_lds_dwordx4 v[144:145], off
	s_setprio 1
	s_waitcnt vmcnt(8) lgkmcnt(0)
	s_barrier
	v_mfma_f32_16x16x32_bf16 v[124:127], v[152:155], v[184:187], v[124:127]
	v_mfma_f32_16x16x32_bf16 v[116:119], v[160:163], v[184:187], v[116:119]
	v_mfma_f32_16x16x32_bf16 v[108:111], v[152:155], v[192:195], v[108:111]
	v_mfma_f32_16x16x32_bf16 v[100:103], v[160:163], v[192:195], v[100:103]
	v_mfma_f32_16x16x32_bf16 v[92:95], v[152:155], v[200:203], v[92:95]
	v_mfma_f32_16x16x32_bf16 v[84:87], v[160:163], v[200:203], v[84:87]
	v_mfma_f32_16x16x32_bf16 v[76:79], v[152:155], v[208:211], v[76:79]
	v_mfma_f32_16x16x32_bf16 v[68:71], v[160:163], v[208:211], v[68:71]
	v_mfma_f32_16x16x32_bf16 v[124:127], v[156:159], v[188:191], v[124:127]
	v_mfma_f32_16x16x32_bf16 v[116:119], v[164:167], v[188:191], v[116:119]
	v_mfma_f32_16x16x32_bf16 v[108:111], v[156:159], v[196:199], v[108:111]
	v_mfma_f32_16x16x32_bf16 v[100:103], v[164:167], v[196:199], v[100:103]
	v_mfma_f32_16x16x32_bf16 v[92:95], v[156:159], v[204:207], v[92:95]
	v_mfma_f32_16x16x32_bf16 v[84:87], v[164:167], v[204:207], v[84:87]
	v_mfma_f32_16x16x32_bf16 v[76:79], v[156:159], v[212:215], v[76:79]
	v_mfma_f32_16x16x32_bf16 v[68:71], v[164:167], v[212:215], v[68:71]
	v_mfma_f32_16x16x32_bf16 v[120:123], v[168:171], v[184:187], v[120:123]
	v_mfma_f32_16x16x32_bf16 v[112:115], v[176:179], v[184:187], v[112:115]
	v_mfma_f32_16x16x32_bf16 v[104:107], v[168:171], v[192:195], v[104:107]
	v_mfma_f32_16x16x32_bf16 v[96:99], v[176:179], v[192:195], v[96:99]
	v_mfma_f32_16x16x32_bf16 v[88:91], v[168:171], v[200:203], v[88:91]
	v_mfma_f32_16x16x32_bf16 v[80:83], v[176:179], v[200:203], v[80:83]
	v_mfma_f32_16x16x32_bf16 v[72:75], v[168:171], v[208:211], v[72:75]
	v_mfma_f32_16x16x32_bf16 v[64:67], v[176:179], v[208:211], v[64:67]
	v_mfma_f32_16x16x32_bf16 v[120:123], v[172:175], v[188:191], v[120:123]
	v_mfma_f32_16x16x32_bf16 v[112:115], v[180:183], v[188:191], v[112:115]
	v_mfma_f32_16x16x32_bf16 v[104:107], v[172:175], v[196:199], v[104:107]
	v_mfma_f32_16x16x32_bf16 v[96:99], v[180:183], v[196:199], v[96:99]
	v_mfma_f32_16x16x32_bf16 v[88:91], v[172:175], v[204:207], v[88:91]
	v_mfma_f32_16x16x32_bf16 v[80:83], v[180:183], v[204:207], v[80:83]
	s_barrier
	v_mfma_f32_16x16x32_bf16 v[72:75], v[172:175], v[212:215], v[72:75]
	v_mfma_f32_16x16x32_bf16 v[64:67], v[180:183], v[212:215], v[64:67]
	s_setprio 0
	s_add_i32 s77, s65, s38
	v_lshl_add_u64 v[144:145], s[30:31], 0, v[132:133]
	s_mov_b32 m0, s77
	ds_read_b128 v[184:187], v150 offset:16384
	ds_read_b128 v[188:191], v150 offset:17408
	ds_read_b128 v[192:195], v150 offset:18432
	ds_read_b128 v[196:199], v150 offset:19456
	ds_read_b128 v[200:203], v150 offset:20480
	ds_read_b128 v[204:207], v150 offset:21504
	ds_read_b128 v[208:211], v150 offset:22528
	ds_read_b128 v[212:215], v150 offset:23552
	global_load_lds_dwordx4 v[144:145], off
	s_add_i32 m0, s77, 0x2000
	s_add_u32 s78, s30, 0x80000
	v_lshl_add_u64 v[216:217], s[30:31], 0, v[128:129]
	s_addc_u32 s79, s31, 0
	s_add_i32 s77, s66, s38
	global_load_lds_dwordx4 v[216:217], off
	v_lshl_add_u64 v[218:219], s[78:79], 0, v[132:133]
	s_mov_b32 m0, s77
	v_lshl_add_u64 v[220:221], s[34:35], 0, v[130:131]
	global_load_lds_dwordx4 v[218:219], off
	v_lshl_add_u64 v[218:219], s[78:79], 0, v[128:129]
	s_add_i32 m0, s77, 0x2000
	s_nop 0
	global_load_lds_dwordx4 v[218:219], off
	v_lshl_add_u64 v[218:219], s[34:35], 0, v[134:135]
	s_mov_b32 m0, s25
	s_nop 0
	global_load_lds_dwordx4 v[218:219], off
	s_mov_b32 m0, s27
	s_nop 0
	global_load_lds_dwordx4 v[220:221], off
	s_setprio 1
	s_waitcnt vmcnt(8) lgkmcnt(0)
	s_barrier
; #define PG8_STAGE(bufoff, gbase, voff) do { _Pragma("unroll") for (int _i = 0; _i < 2; ++_i) \
;         __builtin_amdgcn_global_load_lds((const unsigned*)((const char*)(gbase) + (voff)[_i]), (LAS unsigned*)(lds + (bufoff) + ldsw + _i * 8192), 16, 0, 0); } while (0)
; #define PG8_LDA(dst, b, h) do { _Pragma("unroll") for (int m = 0; m < 4; ++m) _Pragma("unroll") for (int k = 0; k < 2; ++k) dst[m][k] = *(const LAS bf16x8*)(lds + PG8_SA(b, h) + aoff + m * 2048 + k * KOFF); } while (0)
; #define PG8_LDB(dst, b, h) do { _Pragma("unroll") for (int n = 0; n < 2; ++n) _Pragma("unroll") for (int k = 0; k < 2; ++k) dst[n][k] = *(const LAS bf16x8*)(lds + PG8_SB(b, h) + boff + n * 2048 + k * KOFF); } while (0)
; #define PG8_WAIT_V(n) asm volatile("s_waitcnt vmcnt(" #n ")" ::: "memory")
; #define PG8_WAIT_L(n) asm volatile("s_waitcnt lgkmcnt(" #n ")" ::: "memory")
; #define PG8_BAR __builtin_amdgcn_s_barrier()
; #define PG8_SCHED __builtin_amdgcn_sched_barrier(0)
; template <class Epi, bool ALIGN_EPI = true, bool FP8 = false>
; __device__ __forceinline__ void gemm_phase(LAS unsigned char* lds, const Gemm g, const StaticOrder& S, const Epi& E, const int wid) {
;     ...
;             PG8_WAIT_V(8); PG8_WAIT_L(0); PG8_BAR; PG8_MMA(1, 0, At, B0); PG8_MMA(1, 1, At, B1); PG8_BAR; PG8_SCHED;
;             PG8_LDB(B0, 1, 0); PG8_LDB(B1, 1, 1); PG8_SCHED; PG8_LDA(At, 1, 0); PG8_STAGE(PG8_SA(0, 1), a2 + hstep, voffA);
;             PG8_WAIT_V(8); PG8_WAIT_L(0); PG8_BAR; PG8_MMA(0, 0, At, B0); PG8_MMA(0, 1, At, B1); PG8_BAR; PG8_SCHED;
	v_mfma_f32_16x16x32_bf16 v[60:63], v[152:155], v[184:187], v[60:63]
	v_mfma_f32_16x16x32_bf16 v[52:55], v[160:163], v[184:187], v[52:55]
	v_mfma_f32_16x16x32_bf16 v[44:47], v[152:155], v[192:195], v[44:47]
	v_mfma_f32_16x16x32_bf16 v[36:39], v[160:163], v[192:195], v[36:39]
	v_mfma_f32_16x16x32_bf16 v[28:31], v[152:155], v[200:203], v[28:31]
	v_mfma_f32_16x16x32_bf16 v[20:23], v[160:163], v[200:203], v[20:23]
	v_mfma_f32_16x16x32_bf16 v[12:15], v[152:155], v[208:211], v[12:15]
	v_mfma_f32_16x16x32_bf16 v[4:7], v[160:163], v[208:211], v[4:7]
	v_mfma_f32_16x16x32_bf16 v[60:63], v[156:159], v[188:191], v[60:63]
	v_mfma_f32_16x16x32_bf16 v[52:55], v[164:167], v[188:191], v[52:55]
	v_mfma_f32_16x16x32_bf16 v[44:47], v[156:159], v[196:199], v[44:47]
	v_mfma_f32_16x16x32_bf16 v[36:39], v[164:167], v[196:199], v[36:39]
	v_mfma_f32_16x16x32_bf16 v[28:31], v[156:159], v[204:207], v[28:31]
	v_mfma_f32_16x16x32_bf16 v[20:23], v[164:167], v[204:207], v[20:23]
	v_mfma_f32_16x16x32_bf16 v[12:15], v[156:159], v[212:215], v[12:15]
	v_mfma_f32_16x16x32_bf16 v[4:7], v[164:167], v[212:215], v[4:7]
	v_mfma_f32_16x16x32_bf16 v[56:59], v[168:171], v[184:187], v[56:59]
	v_mfma_f32_16x16x32_bf16 v[48:51], v[176:179], v[184:187], v[48:51]
	v_mfma_f32_16x16x32_bf16 v[40:43], v[168:171], v[192:195], v[40:43]
	v_mfma_f32_16x16x32_bf16 v[32:35], v[176:179], v[192:195], v[32:35]
	v_mfma_f32_16x16x32_bf16 v[24:27], v[168:171], v[200:203], v[24:27]
	v_mfma_f32_16x16x32_bf16 v[16:19], v[176:179], v[200:203], v[16:19]
	v_mfma_f32_16x16x32_bf16 v[8:11], v[168:171], v[208:211], v[8:11]
	v_mfma_f32_16x16x32_bf16 v[0:3], v[176:179], v[208:211], v[0:3]
	v_mfma_f32_16x16x32_bf16 v[56:59], v[172:175], v[188:191], v[56:59]
	v_mfma_f32_16x16x32_bf16 v[48:51], v[180:183], v[188:191], v[48:51]
	v_mfma_f32_16x16x32_bf16 v[40:43], v[172:175], v[196:199], v[40:43]
	v_mfma_f32_16x16x32_bf16 v[32:35], v[180:183], v[196:199], v[32:35]
	v_mfma_f32_16x16x32_bf16 v[24:27], v[172:175], v[204:207], v[24:27]
	v_mfma_f32_16x16x32_bf16 v[16:19], v[180:183], v[204:207], v[16:19]
	s_barrier
	v_mfma_f32_16x16x32_bf16 v[8:11], v[172:175], v[212:215], v[8:11]
	v_mfma_f32_16x16x32_bf16 v[0:3], v[180:183], v[212:215], v[0:3]
	s_setprio 0
	s_add_i32 s77, 0, 0x18000
	s_add_i32 s78, 0, 0x1c000
	v_add_u32_e32 v164, s77, v147
	v_add_u32_e32 v180, s78, v147
	ds_read_b128 v[152:155], v164
	ds_read_b128 v[156:159], v164 offset:1024
	ds_read_b128 v[160:163], v164 offset:2048
	ds_read_b128 v[164:167], v164 offset:3072
	ds_read_b128 v[168:171], v180
	ds_read_b128 v[172:175], v180 offset:1024
	ds_read_b128 v[176:179], v180 offset:2048
	ds_read_b128 v[180:183], v180 offset:3072
	s_add_u32 s34, s34, 0x80000
	s_addc_u32 s35, s35, 0
	s_mov_b32 m0, s39
	v_lshl_add_u64 v[222:223], s[34:35], 0, v[134:135]
	ds_read_b128 v[184:187], v150 offset:32768
	ds_read_b128 v[188:191], v150 offset:33792
	ds_read_b128 v[192:195], v150 offset:34816
	ds_read_b128 v[196:199], v150 offset:35840
	ds_read_b128 v[200:203], v150 offset:36864
	ds_read_b128 v[204:207], v150 offset:37888
	ds_read_b128 v[208:211], v150 offset:38912
	ds_read_b128 v[212:215], v150 offset:39936
	global_load_lds_dwordx4 v[222:223], off
	v_lshl_add_u64 v[222:223], s[34:35], 0, v[130:131]
	s_mov_b32 m0, s48
	s_nop 0
	global_load_lds_dwordx4 v[222:223], off
	s_setprio 1
	s_waitcnt vmcnt(8) lgkmcnt(0)
	s_barrier
	v_mfma_f32_16x16x32_bf16 v[124:127], v[152:155], v[184:187], v[124:127]
	v_mfma_f32_16x16x32_bf16 v[116:119], v[160:163], v[184:187], v[116:119]
	v_mfma_f32_16x16x32_bf16 v[108:111], v[152:155], v[192:195], v[108:111]
	v_mfma_f32_16x16x32_bf16 v[100:103], v[160:163], v[192:195], v[100:103]
	v_mfma_f32_16x16x32_bf16 v[92:95], v[152:155], v[200:203], v[92:95]
	v_mfma_f32_16x16x32_bf16 v[84:87], v[160:163], v[200:203], v[84:87]
	v_mfma_f32_16x16x32_bf16 v[76:79], v[152:155], v[208:211], v[76:79]
	v_mfma_f32_16x16x32_bf16 v[68:71], v[160:163], v[208:211], v[68:71]
	v_mfma_f32_16x16x32_bf16 v[124:127], v[156:159], v[188:191], v[124:127]
	v_mfma_f32_16x16x32_bf16 v[116:119], v[164:167], v[188:191], v[116:119]
	v_mfma_f32_16x16x32_bf16 v[108:111], v[156:159], v[196:199], v[108:111]
	v_mfma_f32_16x16x32_bf16 v[100:103], v[164:167], v[196:199], v[100:103]
	v_mfma_f32_16x16x32_bf16 v[92:95], v[156:159], v[204:207], v[92:95]
	v_mfma_f32_16x16x32_bf16 v[84:87], v[164:167], v[204:207], v[84:87]
	v_mfma_f32_16x16x32_bf16 v[76:79], v[156:159], v[212:215], v[76:79]
	v_mfma_f32_16x16x32_bf16 v[68:71], v[164:167], v[212:215], v[68:71]
	v_mfma_f32_16x16x32_bf16 v[120:123], v[168:171], v[184:187], v[120:123]
	v_mfma_f32_16x16x32_bf16 v[112:115], v[176:179], v[184:187], v[112:115]
	v_mfma_f32_16x16x32_bf16 v[104:107], v[168:171], v[192:195], v[104:107]
	v_mfma_f32_16x16x32_bf16 v[96:99], v[176:179], v[192:195], v[96:99]
	v_mfma_f32_16x16x32_bf16 v[88:91], v[168:171], v[200:203], v[88:91]
	v_mfma_f32_16x16x32_bf16 v[80:83], v[176:179], v[200:203], v[80:83]
	v_mfma_f32_16x16x32_bf16 v[72:75], v[168:171], v[208:211], v[72:75]
	v_mfma_f32_16x16x32_bf16 v[64:67], v[176:179], v[208:211], v[64:67]
	v_mfma_f32_16x16x32_bf16 v[120:123], v[172:175], v[188:191], v[120:123]
	v_mfma_f32_16x16x32_bf16 v[112:115], v[180:183], v[188:191], v[112:115]
	v_mfma_f32_16x16x32_bf16 v[104:107], v[172:175], v[196:199], v[104:107]
	v_mfma_f32_16x16x32_bf16 v[96:99], v[180:183], v[196:199], v[96:99]
	v_mfma_f32_16x16x32_bf16 v[88:91], v[172:175], v[204:207], v[88:91]
	v_mfma_f32_16x16x32_bf16 v[80:83], v[180:183], v[204:207], v[80:83]
	s_barrier
; #define PG8_STAGE(bufoff, gbase, voff) do { _Pragma("unroll") for (int _i = 0; _i < 2; ++_i) \
;         __builtin_amdgcn_global_load_lds((const unsigned*)((const char*)(gbase) + (voff)[_i]), (LAS unsigned*)(lds + (bufoff) + ldsw + _i * 8192), 16, 0, 0); } while (0)
; #define PG8_LDA(dst, b, h) do { _Pragma("unroll") for (int m = 0; m < 4; ++m) _Pragma("unroll") for (int k = 0; k < 2; ++k) dst[m][k] = *(const LAS bf16x8*)(lds + PG8_SA(b, h) + aoff + m * 2048 + k * KOFF); } while (0)
; #define PG8_WAIT_V(n) asm volatile("s_waitcnt vmcnt(" #n ")" ::: "memory")
; #define PG8_WAIT_L(n) asm volatile("s_waitcnt lgkmcnt(" #n ")" ::: "memory")
; #define PG8_BAR __builtin_amdgcn_s_barrier()
; #define PG8_SCHED __builtin_amdgcn_sched_barrier(0)
; template <class Epi, bool ALIGN_EPI = true, bool FP8 = false>
; __device__ __forceinline__ void gemm_phase(LAS unsigned char* lds, const Gemm g, const StaticOrder& S, const Epi& E, const int wid) {
;     ...
;             PG8_WAIT_V(8); PG8_WAIT_L(0); PG8_BAR; PG8_MMA(0, 0, At, B0); PG8_MMA(0, 1, At, B1); PG8_BAR; PG8_SCHED;
;             PG8_LDA(At, 1, 1); PG8_STAGE(PG8_SB(1, 0), b3, voffB); PG8_STAGE(PG8_SB(1, 1), b3 + hstep, voffB); PG8_STAGE(PG8_SA(1, 0), a3, voffA);
;             PG8_WAIT_V(8); PG8_WAIT_L(0); PG8_BAR; PG8_MMA(1, 0, At, B0); PG8_MMA(1, 1, At, B1); PG8_BAR; PG8_SCHED;
;         }
	v_mfma_f32_16x16x32_bf16 v[72:75], v[172:175], v[212:215], v[72:75]
	v_mfma_f32_16x16x32_bf16 v[64:67], v[180:183], v[212:215], v[64:67]
	s_setprio 0
	s_add_i32 s34, s77, s38
	v_lshl_add_u64 v[144:145], v[144:145], 0, s[14:15]
	s_mov_b32 m0, s34
	ds_read_b128 v[184:187], v150 offset:49152
	ds_read_b128 v[188:191], v150 offset:50176
	ds_read_b128 v[192:195], v150 offset:51200
	ds_read_b128 v[196:199], v150 offset:52224
	ds_read_b128 v[200:203], v150 offset:53248
	ds_read_b128 v[204:207], v150 offset:54272
	ds_read_b128 v[208:211], v150 offset:55296
	ds_read_b128 v[212:215], v150 offset:56320
	global_load_lds_dwordx4 v[144:145], off
	s_add_i32 m0, s34, 0x2000
	s_add_u32 s30, s30, 0x80080
	v_lshl_add_u64 v[144:145], v[216:217], 0, s[14:15]
	s_addc_u32 s31, s31, 0
	s_add_i32 s34, s78, s38
	global_load_lds_dwordx4 v[144:145], off
	v_lshl_add_u64 v[144:145], s[30:31], 0, v[132:133]
	s_mov_b32 m0, s34
	s_nop 0
	global_load_lds_dwordx4 v[144:145], off
	v_lshl_add_u64 v[144:145], s[30:31], 0, v[128:129]
	s_add_i32 m0, s34, 0x2000
	s_nop 0
	global_load_lds_dwordx4 v[144:145], off
	v_lshl_add_u64 v[144:145], v[218:219], 0, s[14:15]
	s_mov_b32 m0, s53
	s_nop 0
	global_load_lds_dwordx4 v[144:145], off
	v_lshl_add_u64 v[144:145], v[220:221], 0, s[14:15]
	s_mov_b32 m0, s55
	s_nop 0
	global_load_lds_dwordx4 v[144:145], off
	s_setprio 1
	s_waitcnt vmcnt(8) lgkmcnt(0)
	s_barrier
	v_mfma_f32_16x16x32_bf16 v[60:63], v[152:155], v[184:187], v[60:63]
	v_mfma_f32_16x16x32_bf16 v[52:55], v[160:163], v[184:187], v[52:55]
	v_mfma_f32_16x16x32_bf16 v[44:47], v[152:155], v[192:195], v[44:47]
	v_mfma_f32_16x16x32_bf16 v[36:39], v[160:163], v[192:195], v[36:39]
	v_mfma_f32_16x16x32_bf16 v[28:31], v[152:155], v[200:203], v[28:31]
	v_mfma_f32_16x16x32_bf16 v[20:23], v[160:163], v[200:203], v[20:23]
	v_mfma_f32_16x16x32_bf16 v[12:15], v[152:155], v[208:211], v[12:15]
	v_mfma_f32_16x16x32_bf16 v[4:7], v[160:163], v[208:211], v[4:7]
	v_mfma_f32_16x16x32_bf16 v[60:63], v[156:159], v[188:191], v[60:63]
	v_mfma_f32_16x16x32_bf16 v[52:55], v[164:167], v[188:191], v[52:55]
	v_mfma_f32_16x16x32_bf16 v[44:47], v[156:159], v[196:199], v[44:47]
	v_mfma_f32_16x16x32_bf16 v[36:39], v[164:167], v[196:199], v[36:39]
	v_mfma_f32_16x16x32_bf16 v[28:31], v[156:159], v[204:207], v[28:31]
	v_mfma_f32_16x16x32_bf16 v[20:23], v[164:167], v[204:207], v[20:23]
	v_mfma_f32_16x16x32_bf16 v[12:15], v[156:159], v[212:215], v[12:15]
	v_mfma_f32_16x16x32_bf16 v[4:7], v[164:167], v[212:215], v[4:7]
	v_mfma_f32_16x16x32_bf16 v[56:59], v[168:171], v[184:187], v[56:59]
	v_mfma_f32_16x16x32_bf16 v[48:51], v[176:179], v[184:187], v[48:51]
	v_mfma_f32_16x16x32_bf16 v[40:43], v[168:171], v[192:195], v[40:43]
	v_mfma_f32_16x16x32_bf16 v[32:35], v[176:179], v[192:195], v[32:35]
	v_mfma_f32_16x16x32_bf16 v[24:27], v[168:171], v[200:203], v[24:27]
	v_mfma_f32_16x16x32_bf16 v[16:19], v[176:179], v[200:203], v[16:19]
	v_mfma_f32_16x16x32_bf16 v[8:11], v[168:171], v[208:211], v[8:11]
	v_mfma_f32_16x16x32_bf16 v[0:3], v[176:179], v[208:211], v[0:3]
	v_mfma_f32_16x16x32_bf16 v[56:59], v[172:175], v[188:191], v[56:59]
	v_mfma_f32_16x16x32_bf16 v[48:51], v[180:183], v[188:191], v[48:51]
	v_mfma_f32_16x16x32_bf16 v[40:43], v[172:175], v[196:199], v[40:43]
	v_mfma_f32_16x16x32_bf16 v[32:35], v[180:183], v[196:199], v[32:35]
	v_mfma_f32_16x16x32_bf16 v[24:27], v[172:175], v[204:207], v[24:27]
	v_mfma_f32_16x16x32_bf16 v[16:19], v[180:183], v[204:207], v[16:19]
	s_barrier
	v_mfma_f32_16x16x32_bf16 v[8:11], v[172:175], v[212:215], v[8:11]
	v_mfma_f32_16x16x32_bf16 v[0:3], v[180:183], v[212:215], v[0:3]
	s_setprio 0
	s_add_u32 s28, s28, 0x100
	s_addc_u32 s29, s29, 0
	s_add_u32 s52, s52, 0x100
	s_addc_u32 s75, s75, 0
	s_cmp_ge_u32 s76, s54
	s_mov_b32 s30, s76
	s_cbranch_scc0 .LBB0_2452
	s_and_b64 vcc, exec, s[12:13]
	s_cbranch_vccz .LBB0_2455

; #define PG8_STAGE(bufoff, gbase, voff) do { _Pragma("unroll") for (int _i = 0; _i < 2; ++_i) \
;         __builtin_amdgcn_global_load_lds((const unsigned*)((const char*)(gbase) + (voff)[_i]), (LAS unsigned*)(lds + (bufoff) + ldsw + _i * 8192), 16, 0, 0); } while (0)
; #define PG8_LDA(dst, b, h) do { _Pragma("unroll") for (int m = 0; m < 4; ++m) _Pragma("unroll") for (int k = 0; k < 2; ++k) dst[m][k] = *(const LAS bf16x8*)(lds + PG8_SA(b, h) + aoff + m * 2048 + k * KOFF); } while (0)
; #define PG8_LDB(dst, b, h) do { _Pragma("unroll") for (int n = 0; n < 2; ++n) _Pragma("unroll") for (int k = 0; k < 2; ++k) dst[n][k] = *(const LAS bf16x8*)(lds + PG8_SB(b, h) + boff + n * 2048 + k * KOFF); } while (0)
; #define PG8_WAIT_V(n) asm volatile("s_waitcnt vmcnt(" #n ")" ::: "memory")
; #define PG8_WAIT_L(n) asm volatile("s_waitcnt lgkmcnt(" #n ")" ::: "memory")
; #define PG8_BAR __builtin_amdgcn_s_barrier()
; #define PG8_SCHED __builtin_amdgcn_sched_barrier(0)
; template <class Epi, bool ALIGN_EPI = true, bool FP8 = false>
; __device__ __forceinline__ void gemm_phase(LAS unsigned char* lds, const Gemm g, const StaticOrder& S, const Epi& E, const int wid) {
;     ...
;             const char* a1 = cA + (size_t)(t + 1) * kstep;
;             const char* a2 = last ? nA : cA + (size_t)(t + 2) * kstep; const char* b2 = last ? nB : cB + (size_t)(t + 2) * kstep;
;             const char* a3 = a2 + kstep; const char* b3 = b2 + kstep;
;             PG8_LDB(B0, 0, 0); PG8_LDB(B1, 0, 1); PG8_SCHED; PG8_LDA(At, 0, 0); PG8_STAGE(PG8_SA(1, 1), a1 + hstep, voffA);
;             PG8_WAIT_V(8); PG8_WAIT_L(0); PG8_BAR; PG8_MMA(0, 0, At, B0); PG8_MMA(0, 1, At, B1); PG8_BAR; PG8_SCHED;
;             PG8_LDA(At, 0, 1); PG8_STAGE(PG8_SB(0, 0), b2, voffB); PG8_STAGE(PG8_SB(0, 1), b2 + hstep, voffB); PG8_STAGE(PG8_SA(0, 0), a2, voffA);
;             PG8_WAIT_V(8); PG8_WAIT_L(0); PG8_BAR; PG8_MMA(1, 0, At, B0); PG8_MMA(1, 1, At, B1); PG8_BAR; PG8_SCHED;
.LBB0_2536:
	ds_read_b128 v[152:155], v188
	ds_read_b128 v[156:159], v188 offset:1024
	ds_read_b128 v[144:147], v188 offset:2048
	ds_read_b128 v[148:151], v188 offset:3072
	ds_read_b128 v[136:139], v189
	ds_read_b128 v[140:143], v189 offset:1024
	ds_read_b128 v[128:131], v189 offset:2048
	ds_read_b128 v[132:135], v189 offset:3072
	s_add_i32 s42, s26, 2
	s_add_u32 s27, s24, 0xfff50080
	s_addc_u32 s28, s25, -1
	s_cmp_eq_u32 s81, s26
	s_cselect_b32 s26, s20, s82
	s_cselect_b32 s29, s7, s28
	s_cselect_b32 s28, s6, s27
	s_cselect_b32 s27, s21, s83
	v_lshl_add_u64 v[216:217], s[24:25], 0, v[172:173]
	s_add_i32 m0, s34, 0xc000
	ds_read_b128 v[178:181], v190
	ds_read_b128 v[182:185], v190 offset:1024
	ds_read_b128 v[192:195], v190 offset:2048
	ds_read_b128 v[196:199], v190 offset:3072
	ds_read_b128 v[200:203], v190 offset:4096
	ds_read_b128 v[204:207], v190 offset:5120
	ds_read_b128 v[208:211], v190 offset:6144
	ds_read_b128 v[212:215], v190 offset:7168
	global_load_lds_dwordx4 v[216:217], off
	v_lshl_add_u64 v[216:217], s[24:25], 0, v[174:175]
	s_add_i32 m0, s34, 0xe000
	s_nop 0
	global_load_lds_dwordx4 v[216:217], off
	s_setprio 1
	s_waitcnt vmcnt(8) lgkmcnt(0)
	s_barrier
	v_mfma_f32_16x16x128_f8f6f4 v[120:123], v[152:159], v[178:185], v[120:123]
	v_mfma_f32_16x16x128_f8f6f4 v[124:127], v[144:151], v[178:185], v[124:127]
	v_mfma_f32_16x16x128_f8f6f4 v[112:115], v[152:159], v[192:199], v[112:115]
	v_mfma_f32_16x16x128_f8f6f4 v[116:119], v[144:151], v[192:199], v[116:119]
	v_mfma_f32_16x16x128_f8f6f4 v[96:99], v[152:159], v[200:207], v[96:99]
	v_mfma_f32_16x16x128_f8f6f4 v[100:103], v[144:151], v[200:207], v[100:103]
	v_mfma_f32_16x16x128_f8f6f4 v[80:83], v[152:159], v[208:215], v[80:83]
	v_mfma_f32_16x16x128_f8f6f4 v[84:87], v[144:151], v[208:215], v[84:87]
	v_mfma_f32_16x16x128_f8f6f4 v[104:107], v[136:143], v[178:185], v[104:107]
	v_mfma_f32_16x16x128_f8f6f4 v[108:111], v[128:135], v[178:185], v[108:111]
	v_mfma_f32_16x16x128_f8f6f4 v[88:91], v[136:143], v[192:199], v[88:91]
	v_mfma_f32_16x16x128_f8f6f4 v[92:95], v[128:135], v[192:199], v[92:95]
	v_mfma_f32_16x16x128_f8f6f4 v[72:75], v[136:143], v[200:207], v[72:75]
	v_mfma_f32_16x16x128_f8f6f4 v[76:79], v[128:135], v[200:207], v[76:79]
	s_barrier
	v_mfma_f32_16x16x128_f8f6f4 v[64:67], v[136:143], v[208:215], v[64:67]
	v_mfma_f32_16x16x128_f8f6f4 v[68:71], v[128:135], v[208:215], v[68:71]
	s_setprio 0
	s_add_i32 s43, s64, s31
	v_lshl_add_u64 v[178:179], s[26:27], 0, v[162:163]
	s_mov_b32 m0, s43
	ds_read_b128 v[192:195], v190 offset:16384
	ds_read_b128 v[196:199], v190 offset:17408
	ds_read_b128 v[200:203], v190 offset:18432
	ds_read_b128 v[204:207], v190 offset:19456
	ds_read_b128 v[208:211], v190 offset:20480
	ds_read_b128 v[212:215], v190 offset:21504
	ds_read_b128 v[216:219], v190 offset:22528
	ds_read_b128 v[220:223], v190 offset:23552
	global_load_lds_dwordx4 v[178:179], off
	s_add_i32 m0, s43, 0x2000
	s_add_u32 s84, s26, 0xb0000
	v_lshl_add_u64 v[180:181], s[26:27], 0, v[166:167]
	s_addc_u32 s85, s27, 0
	s_add_i32 s43, s65, s31
	global_load_lds_dwordx4 v[180:181], off
	v_lshl_add_u64 v[182:183], s[84:85], 0, v[162:163]
	s_mov_b32 m0, s43
	v_lshl_add_u64 v[184:185], s[28:29], 0, v[164:165]
	global_load_lds_dwordx4 v[182:183], off
	v_lshl_add_u64 v[182:183], s[84:85], 0, v[166:167]
	s_add_i32 m0, s43, 0x2000
	s_nop 0
	global_load_lds_dwordx4 v[182:183], off
	v_lshl_add_u64 v[182:183], s[28:29], 0, v[160:161]
	s_mov_b32 m0, s34
	s_nop 0
	global_load_lds_dwordx4 v[182:183], off
	s_mov_b32 m0, s35
	s_nop 0
	global_load_lds_dwordx4 v[184:185], off
	s_setprio 1
	s_waitcnt vmcnt(8) lgkmcnt(0)
	s_barrier
	v_mfma_f32_16x16x128_f8f6f4 v[56:59], v[152:159], v[192:199], v[56:59]
	v_mfma_f32_16x16x128_f8f6f4 v[60:63], v[144:151], v[192:199], v[60:63]
	v_mfma_f32_16x16x128_f8f6f4 v[48:51], v[152:159], v[200:207], v[48:51]
	v_mfma_f32_16x16x128_f8f6f4 v[52:55], v[144:151], v[200:207], v[52:55]
	v_mfma_f32_16x16x128_f8f6f4 v[32:35], v[152:159], v[208:215], v[32:35]
	v_mfma_f32_16x16x128_f8f6f4 v[224:227], v[144:151], v[208:215], v[36:39]
	v_mfma_f32_16x16x128_f8f6f4 v[228:231], v[152:159], v[216:223], v[16:19]
	v_mfma_f32_16x16x128_f8f6f4 v[232:235], v[144:151], v[216:223], v[20:23]
	v_mfma_f32_16x16x128_f8f6f4 v[44:47], v[128:135], v[192:199], v[44:47]
	v_mfma_f32_16x16x128_f8f6f4 v[236:239], v[136:143], v[192:199], v[40:43]
	v_mfma_f32_16x16x128_f8f6f4 v[240:243], v[136:143], v[200:207], v[24:27]
	v_mfma_f32_16x16x128_f8f6f4 v[200:203], v[128:135], v[200:207], v[28:31]
	v_mfma_f32_16x16x128_f8f6f4 v[204:207], v[136:143], v[208:215], v[8:11]
	v_mfma_f32_16x16x128_f8f6f4 v[208:211], v[128:135], v[208:215], v[12:15]
	s_barrier
; #define PG8_STAGE(bufoff, gbase, voff) do { _Pragma("unroll") for (int _i = 0; _i < 2; ++_i) \
;         __builtin_amdgcn_global_load_lds((const unsigned*)((const char*)(gbase) + (voff)[_i]), (LAS unsigned*)(lds + (bufoff) + ldsw + _i * 8192), 16, 0, 0); } while (0)
; #define PG8_LDA(dst, b, h) do { _Pragma("unroll") for (int m = 0; m < 4; ++m) _Pragma("unroll") for (int k = 0; k < 2; ++k) dst[m][k] = *(const LAS bf16x8*)(lds + PG8_SA(b, h) + aoff + m * 2048 + k * KOFF); } while (0)
; #define PG8_LDB(dst, b, h) do { _Pragma("unroll") for (int n = 0; n < 2; ++n) _Pragma("unroll") for (int k = 0; k < 2; ++k) dst[n][k] = *(const LAS bf16x8*)(lds + PG8_SB(b, h) + boff + n * 2048 + k * KOFF); } while (0)
; #define PG8_WAIT_V(n) asm volatile("s_waitcnt vmcnt(" #n ")" ::: "memory")
; #define PG8_WAIT_L(n) asm volatile("s_waitcnt lgkmcnt(" #n ")" ::: "memory")
; #define PG8_BAR __builtin_amdgcn_s_barrier()
; #define PG8_SCHED __builtin_amdgcn_sched_barrier(0)
; template <class Epi, bool ALIGN_EPI = true, bool FP8 = false>
; __device__ __forceinline__ void gemm_phase(LAS unsigned char* lds, const Gemm g, const StaticOrder& S, const Epi& E, const int wid) {
;     ...
;             PG8_WAIT_V(8); PG8_WAIT_L(0); PG8_BAR; PG8_MMA(1, 0, At, B0); PG8_MMA(1, 1, At, B1); PG8_BAR; PG8_SCHED;
;             PG8_LDB(B0, 1, 0); PG8_LDB(B1, 1, 1); PG8_SCHED; PG8_LDA(At, 1, 0); PG8_STAGE(PG8_SA(0, 1), a2 + hstep, voffA);
;             PG8_WAIT_V(8); PG8_WAIT_L(0); PG8_BAR; PG8_MMA(0, 0, At, B0); PG8_MMA(0, 1, At, B1); PG8_BAR; PG8_SCHED;
;             PG8_LDA(At, 1, 1); PG8_STAGE(PG8_SB(1, 0), b3, voffB); PG8_STAGE(PG8_SB(1, 1), b3 + hstep, voffB); PG8_STAGE(PG8_SA(1, 0), a3, voffA);
;             PG8_WAIT_V(8); PG8_WAIT_L(0); PG8_BAR; PG8_MMA(1, 0, At, B0); PG8_MMA(1, 1, At, B1); PG8_BAR; PG8_SCHED;
;         }
	v_mfma_f32_16x16x128_f8f6f4 v[212:215], v[136:143], v[216:223], v[0:3]
	v_mfma_f32_16x16x128_f8f6f4 v[216:219], v[128:135], v[216:223], v[4:7]
	s_setprio 0
	s_add_i32 s43, 0, 0x18000
	s_add_i32 s54, 0, 0x1c000
	s_nop 0
	v_add_u32_e32 v12, s43, v187
	v_add_u32_e32 v16, s54, v187
	ds_read_b128 v[0:3], v12
	ds_read_b128 v[4:7], v12 offset:1024
	ds_read_b128 v[8:11], v12 offset:2048
	ds_read_b128 v[12:15], v12 offset:3072
	ds_read_b128 v[128:131], v16
	ds_read_b128 v[132:135], v16 offset:1024
	ds_read_b128 v[136:139], v16 offset:2048
	ds_read_b128 v[140:143], v16 offset:3072
	s_add_u32 s28, s28, 0xb0000
	s_addc_u32 s29, s29, 0
	s_mov_b32 m0, s36
	v_lshl_add_u64 v[152:153], s[28:29], 0, v[160:161]
	ds_read_b128 v[16:19], v190 offset:32768
	ds_read_b128 v[20:23], v190 offset:33792
	ds_read_b128 v[24:27], v190 offset:34816
	ds_read_b128 v[28:31], v190 offset:35840
	ds_read_b128 v[36:39], v190 offset:36864
	ds_read_b128 v[40:43], v190 offset:37888
	ds_read_b128 v[144:147], v190 offset:38912
	ds_read_b128 v[148:151], v190 offset:39936
	global_load_lds_dwordx4 v[152:153], off
	v_lshl_add_u64 v[152:153], s[28:29], 0, v[164:165]
	s_mov_b32 m0, s37
	s_nop 0
	global_load_lds_dwordx4 v[152:153], off
	s_setprio 1
	s_waitcnt vmcnt(8) lgkmcnt(0)
	s_barrier
	v_mfma_f32_16x16x128_f8f6f4 v[120:123], v[0:7], v[16:23], v[120:123]
	v_mfma_f32_16x16x128_f8f6f4 v[124:127], v[8:15], v[16:23], v[124:127]
	v_mfma_f32_16x16x128_f8f6f4 v[112:115], v[0:7], v[24:31], v[112:115]
	v_mfma_f32_16x16x128_f8f6f4 v[116:119], v[8:15], v[24:31], v[116:119]
	v_mfma_f32_16x16x128_f8f6f4 v[96:99], v[0:7], v[36:43], v[96:99]
	v_mfma_f32_16x16x128_f8f6f4 v[100:103], v[8:15], v[36:43], v[100:103]
	v_mfma_f32_16x16x128_f8f6f4 v[80:83], v[0:7], v[144:151], v[80:83]
	v_mfma_f32_16x16x128_f8f6f4 v[84:87], v[8:15], v[144:151], v[84:87]
	v_mfma_f32_16x16x128_f8f6f4 v[104:107], v[128:135], v[16:23], v[104:107]
	v_mfma_f32_16x16x128_f8f6f4 v[108:111], v[136:143], v[16:23], v[108:111]
	v_mfma_f32_16x16x128_f8f6f4 v[88:91], v[128:135], v[24:31], v[88:91]
	v_mfma_f32_16x16x128_f8f6f4 v[92:95], v[136:143], v[24:31], v[92:95]
	v_mfma_f32_16x16x128_f8f6f4 v[72:75], v[128:135], v[36:43], v[72:75]
	v_mfma_f32_16x16x128_f8f6f4 v[76:79], v[136:143], v[36:43], v[76:79]
	s_barrier
	v_mfma_f32_16x16x128_f8f6f4 v[64:67], v[128:135], v[144:151], v[64:67]
	v_mfma_f32_16x16x128_f8f6f4 v[68:71], v[136:143], v[144:151], v[68:71]
	s_setprio 0
	s_add_i32 s28, s43, s31
	v_lshl_add_u64 v[16:17], v[178:179], 0, s[14:15]
	s_mov_b32 m0, s28
	ds_read_b128 v[24:27], v190 offset:49152
	ds_read_b128 v[28:31], v190 offset:50176
	ds_read_b128 v[144:147], v190 offset:51200
	ds_read_b128 v[148:151], v190 offset:52224
	ds_read_b128 v[152:155], v190 offset:53248
	ds_read_b128 v[156:159], v190 offset:54272
	ds_read_b128 v[192:195], v190 offset:55296
	ds_read_b128 v[196:199], v190 offset:56320
	global_load_lds_dwordx4 v[16:17], off
	s_add_i32 m0, s28, 0x2000
	s_add_u32 s26, s26, 0xb0080
	v_lshl_add_u64 v[16:17], v[180:181], 0, s[14:15]
	s_addc_u32 s27, s27, 0
	s_add_i32 s28, s54, s31
	global_load_lds_dwordx4 v[16:17], off
	v_lshl_add_u64 v[16:17], s[26:27], 0, v[162:163]
	s_mov_b32 m0, s28
	s_nop 0
	global_load_lds_dwordx4 v[16:17], off
	v_lshl_add_u64 v[16:17], s[26:27], 0, v[166:167]
	s_add_i32 m0, s28, 0x2000
	s_nop 0
	global_load_lds_dwordx4 v[16:17], off
	v_lshl_add_u64 v[16:17], v[182:183], 0, s[14:15]
	s_mov_b32 m0, s52
	s_nop 0
	global_load_lds_dwordx4 v[16:17], off
	v_lshl_add_u64 v[16:17], v[184:185], 0, s[14:15]
	s_mov_b32 m0, s53
	s_nop 0
	global_load_lds_dwordx4 v[16:17], off
	s_setprio 1
	s_waitcnt vmcnt(8) lgkmcnt(0)
	s_barrier
	v_mfma_f32_16x16x128_f8f6f4 v[56:59], v[0:7], v[24:31], v[56:59]
	v_mfma_f32_16x16x128_f8f6f4 v[60:63], v[8:15], v[24:31], v[60:63]
	v_mfma_f32_16x16x128_f8f6f4 v[48:51], v[0:7], v[144:151], v[48:51]
	v_mfma_f32_16x16x128_f8f6f4 v[52:55], v[8:15], v[144:151], v[52:55]
	v_mfma_f32_16x16x128_f8f6f4 v[32:35], v[0:7], v[152:159], v[32:35]
	v_mfma_f32_16x16x128_f8f6f4 v[36:39], v[8:15], v[152:159], v[224:227]
	v_mfma_f32_16x16x128_f8f6f4 v[16:19], v[0:7], v[192:199], v[228:231]
	v_mfma_f32_16x16x128_f8f6f4 v[20:23], v[8:15], v[192:199], v[232:235]
	v_mfma_f32_16x16x128_f8f6f4 v[40:43], v[128:135], v[24:31], v[236:239]
	v_mfma_f32_16x16x128_f8f6f4 v[44:47], v[136:143], v[24:31], v[44:47]
	v_mfma_f32_16x16x128_f8f6f4 v[24:27], v[128:135], v[144:151], v[240:243]
	v_mfma_f32_16x16x128_f8f6f4 v[28:31], v[136:143], v[144:151], v[200:203]
	v_mfma_f32_16x16x128_f8f6f4 v[8:11], v[128:135], v[152:159], v[204:207]
	v_mfma_f32_16x16x128_f8f6f4 v[12:15], v[136:143], v[152:159], v[208:211]
	s_barrier
	v_mfma_f32_16x16x128_f8f6f4 v[0:3], v[128:135], v[192:199], v[212:215]
	v_mfma_f32_16x16x128_f8f6f4 v[4:7], v[136:143], v[192:199], v[216:219]
	s_setprio 0
	s_add_u32 s24, s24, 0x100
	s_addc_u32 s25, s25, 0
	s_add_u32 s82, s82, 0x100
	s_addc_u32 s83, s83, 0
	s_cmp_ge_u32 s42, s80
	s_mov_b32 s26, s42
	s_cbranch_scc0 .LBB0_2536
	s_and_b64 vcc, exec, s[16:17]
	s_cbranch_vccz .LBB0_2539
	s_barrier
